# nt hint also on the bf16 output stores of the rstd-scale and LoRA GEMM epilogues
# speedup vs baseline: 1.0063x; 1.0016x over previous
.LBB0_522:
	s_add_i32 s72, s78, 2
	s_add_u32 s79, s10, 0x80
	s_addc_u32 vcc_lo, s11, 0
	v_add_u32_e32 v148, 0x10000, v185
	s_cmp_eq_u32 s15, s78
	s_cselect_b32 s78, s12, s84
	s_cselect_b32 vcc_hi, s49, vcc_lo
	s_cselect_b32 vcc_lo, s48, s79
	s_cselect_b32 s79, s13, s85
	ds_read_b128 v[128:131], v148 offset:0
	ds_read_b128 v[132:135], v148 offset:1024
	ds_read_b128 v[136:139], v148 offset:2048
	ds_read_b128 v[140:143], v148 offset:3072
	ds_read_b128 v[218:221], v148 offset:16384
	ds_read_b128 v[222:225], v148 offset:17408
	ds_read_b128 v[226:229], v148 offset:18432
	ds_read_b128 v[230:233], v148 offset:19456
	ds_read_b128 v[162:165], v188 offset:0
	ds_read_b128 v[190:193], v188 offset:1024
	ds_read_b128 v[194:197], v188 offset:2048
	ds_read_b128 v[198:201], v188 offset:3072
	ds_read_b128 v[202:205], v188 offset:4096
	ds_read_b128 v[206:209], v188 offset:5120
	ds_read_b128 v[210:213], v188 offset:6144
	ds_read_b128 v[214:217], v188 offset:7168
	s_add_u32 s4, s10, s26
	s_addc_u32 s5, s11, 0
	s_add_i32 m0, s81, 0xc000
	s_nop 0
	global_load_lds_dwordx4 v152, s[4:5]
	s_add_i32 m0, s81, 0xe000
	s_nop 0
	global_load_lds_dwordx4 v144, s[4:5]
	s_waitcnt vmcnt(8)
	s_waitcnt lgkmcnt(0)
	s_barrier
	s_setprio 1
	v_mfma_f32_16x16x32_bf16 v[124:127], v[128:131], v[162:165], v[124:127]
	v_mfma_f32_16x16x32_bf16 v[116:119], v[136:139], v[162:165], v[116:119]
	v_mfma_f32_16x16x32_bf16 v[120:123], v[128:131], v[194:197], v[120:123]
	v_mfma_f32_16x16x32_bf16 v[112:115], v[136:139], v[194:197], v[112:115]
	v_mfma_f32_16x16x32_bf16 v[92:95], v[128:131], v[202:205], v[92:95]
	v_mfma_f32_16x16x32_bf16 v[84:87], v[136:139], v[202:205], v[84:87]
	v_mfma_f32_16x16x32_bf16 v[88:91], v[128:131], v[210:213], v[88:91]
	v_mfma_f32_16x16x32_bf16 v[80:83], v[136:139], v[210:213], v[80:83]
	v_mfma_f32_16x16x32_bf16 v[124:127], v[132:135], v[190:193], v[124:127]
	v_mfma_f32_16x16x32_bf16 v[116:119], v[140:143], v[190:193], v[116:119]
	v_mfma_f32_16x16x32_bf16 v[120:123], v[132:135], v[198:201], v[120:123]
	v_mfma_f32_16x16x32_bf16 v[112:115], v[140:143], v[198:201], v[112:115]
	v_mfma_f32_16x16x32_bf16 v[92:95], v[132:135], v[206:209], v[92:95]
	v_mfma_f32_16x16x32_bf16 v[84:87], v[140:143], v[206:209], v[84:87]
	v_mfma_f32_16x16x32_bf16 v[88:91], v[132:135], v[214:217], v[88:91]
	v_mfma_f32_16x16x32_bf16 v[80:83], v[140:143], v[214:217], v[80:83]
	v_mfma_f32_16x16x32_bf16 v[108:111], v[218:221], v[162:165], v[108:111]
	v_mfma_f32_16x16x32_bf16 v[100:103], v[226:229], v[162:165], v[100:103]
	v_mfma_f32_16x16x32_bf16 v[104:107], v[218:221], v[194:197], v[104:107]
	v_mfma_f32_16x16x32_bf16 v[96:99], v[226:229], v[194:197], v[96:99]
	v_mfma_f32_16x16x32_bf16 v[76:79], v[218:221], v[202:205], v[76:79]
	v_mfma_f32_16x16x32_bf16 v[68:71], v[226:229], v[202:205], v[68:71]
	v_mfma_f32_16x16x32_bf16 v[72:75], v[218:221], v[210:213], v[72:75]
	v_mfma_f32_16x16x32_bf16 v[64:67], v[226:229], v[210:213], v[64:67]
	v_mfma_f32_16x16x32_bf16 v[108:111], v[222:225], v[190:193], v[108:111]
	v_mfma_f32_16x16x32_bf16 v[100:103], v[230:233], v[190:193], v[100:103]
	v_mfma_f32_16x16x32_bf16 v[104:107], v[222:225], v[198:201], v[104:107]
	v_mfma_f32_16x16x32_bf16 v[96:99], v[230:233], v[198:201], v[96:99]
	v_mfma_f32_16x16x32_bf16 v[76:79], v[222:225], v[206:209], v[76:79]
	v_mfma_f32_16x16x32_bf16 v[68:71], v[230:233], v[206:209], v[68:71]
	v_mfma_f32_16x16x32_bf16 v[72:75], v[222:225], v[214:217], v[72:75]
	v_mfma_f32_16x16x32_bf16 v[64:67], v[230:233], v[214:217], v[64:67]
	s_setprio 0
	s_barrier
	ds_read_b128 v[162:165], v188 offset:16384
	ds_read_b128 v[190:193], v188 offset:17408
	ds_read_b128 v[194:197], v188 offset:18432
	ds_read_b128 v[198:201], v188 offset:19456
	ds_read_b128 v[202:205], v188 offset:20480
	ds_read_b128 v[206:209], v188 offset:21504
	ds_read_b128 v[210:213], v188 offset:22528
	ds_read_b128 v[214:217], v188 offset:23552
	s_add_i32 m0, s81, 0x10000
	s_nop 0
	global_load_lds_dwordx4 v154, s[78:79]
	s_add_i32 m0, s81, 0x12000
	s_nop 0
	global_load_lds_dwordx4 v146, s[78:79]
	s_add_i32 m0, s81, 0x0
	s_nop 0
	global_load_lds_dwordx4 v152, vcc
	s_add_i32 m0, s81, 0x2000
	s_nop 0
	global_load_lds_dwordx4 v144, vcc
	s_add_u32 s4, s78, s26
	s_addc_u32 s5, s79, 0
	s_add_i32 m0, s81, 0x14000
	s_nop 0
	global_load_lds_dwordx4 v154, s[4:5]
	s_add_i32 m0, s81, 0x16000
	s_nop 0
	global_load_lds_dwordx4 v146, s[4:5]
	s_waitcnt vmcnt(8)
	s_waitcnt lgkmcnt(0)
	s_barrier
	s_setprio 1
	v_mfma_f32_16x16x32_bf16 v[60:63], v[128:131], v[162:165], v[60:63]
	v_mfma_f32_16x16x32_bf16 v[56:59], v[136:139], v[162:165], v[56:59]
	v_mfma_f32_16x16x32_bf16 v[52:55], v[128:131], v[194:197], v[52:55]
	v_mfma_f32_16x16x32_bf16 v[48:51], v[136:139], v[194:197], v[48:51]
	v_mfma_f32_16x16x32_bf16 v[28:31], v[128:131], v[202:205], v[28:31]
	v_mfma_f32_16x16x32_bf16 v[20:23], v[136:139], v[202:205], v[20:23]
	v_mfma_f32_16x16x32_bf16 v[24:27], v[128:131], v[210:213], v[24:27]
	v_mfma_f32_16x16x32_bf16 v[16:19], v[136:139], v[210:213], v[16:19]
	v_mfma_f32_16x16x32_bf16 v[60:63], v[132:135], v[190:193], v[60:63]
	v_mfma_f32_16x16x32_bf16 v[56:59], v[140:143], v[190:193], v[56:59]
	v_mfma_f32_16x16x32_bf16 v[52:55], v[132:135], v[198:201], v[52:55]
	v_mfma_f32_16x16x32_bf16 v[48:51], v[140:143], v[198:201], v[48:51]
	v_mfma_f32_16x16x32_bf16 v[28:31], v[132:135], v[206:209], v[28:31]
	v_mfma_f32_16x16x32_bf16 v[20:23], v[140:143], v[206:209], v[20:23]
	v_mfma_f32_16x16x32_bf16 v[24:27], v[132:135], v[214:217], v[24:27]
	v_mfma_f32_16x16x32_bf16 v[16:19], v[140:143], v[214:217], v[16:19]
	v_mfma_f32_16x16x32_bf16 v[44:47], v[218:221], v[162:165], v[44:47]
	v_mfma_f32_16x16x32_bf16 v[36:39], v[226:229], v[162:165], v[36:39]
	v_mfma_f32_16x16x32_bf16 v[40:43], v[218:221], v[194:197], v[40:43]
	v_mfma_f32_16x16x32_bf16 v[32:35], v[226:229], v[194:197], v[32:35]
	v_mfma_f32_16x16x32_bf16 v[12:15], v[218:221], v[202:205], v[12:15]
	v_mfma_f32_16x16x32_bf16 v[4:7], v[226:229], v[202:205], v[4:7]
	v_mfma_f32_16x16x32_bf16 v[8:11], v[218:221], v[210:213], v[8:11]
	v_mfma_f32_16x16x32_bf16 v[0:3], v[226:229], v[210:213], v[0:3]
	v_mfma_f32_16x16x32_bf16 v[44:47], v[222:225], v[190:193], v[44:47]
	v_mfma_f32_16x16x32_bf16 v[36:39], v[230:233], v[190:193], v[36:39]
	v_mfma_f32_16x16x32_bf16 v[40:43], v[222:225], v[198:201], v[40:43]
	v_mfma_f32_16x16x32_bf16 v[32:35], v[230:233], v[198:201], v[32:35]
	v_mfma_f32_16x16x32_bf16 v[12:15], v[222:225], v[206:209], v[12:15]
	v_mfma_f32_16x16x32_bf16 v[4:7], v[230:233], v[206:209], v[4:7]
	v_mfma_f32_16x16x32_bf16 v[8:11], v[222:225], v[214:217], v[8:11]
	v_mfma_f32_16x16x32_bf16 v[0:3], v[230:233], v[214:217], v[0:3]
	s_setprio 0
	s_barrier
	ds_read_b128 v[128:131], v148 offset:32768
	ds_read_b128 v[132:135], v148 offset:33792
	ds_read_b128 v[136:139], v148 offset:34816
	ds_read_b128 v[140:143], v148 offset:35840
	ds_read_b128 v[218:221], v148 offset:49152
	ds_read_b128 v[222:225], v148 offset:50176
	ds_read_b128 v[226:229], v148 offset:51200
	ds_read_b128 v[230:233], v148 offset:52224
	ds_read_b128 v[162:165], v188 offset:32768
	ds_read_b128 v[190:193], v188 offset:33792
	ds_read_b128 v[194:197], v188 offset:34816
	ds_read_b128 v[198:201], v188 offset:35840
	ds_read_b128 v[202:205], v188 offset:36864
	ds_read_b128 v[206:209], v188 offset:37888
	ds_read_b128 v[210:213], v188 offset:38912
	ds_read_b128 v[214:217], v188 offset:39936
	s_add_u32 s4, vcc_lo, s26
	s_addc_u32 s5, vcc_hi, 0
	s_add_i32 m0, s81, 0x4000
	s_nop 0
	global_load_lds_dwordx4 v152, s[4:5]
	s_add_i32 m0, s81, 0x6000
	s_nop 0
	global_load_lds_dwordx4 v144, s[4:5]
	s_waitcnt vmcnt(8)
	s_waitcnt lgkmcnt(0)
	s_barrier
	s_setprio 1
	v_mfma_f32_16x16x32_bf16 v[124:127], v[128:131], v[162:165], v[124:127]
	v_mfma_f32_16x16x32_bf16 v[116:119], v[136:139], v[162:165], v[116:119]
	v_mfma_f32_16x16x32_bf16 v[120:123], v[128:131], v[194:197], v[120:123]
	v_mfma_f32_16x16x32_bf16 v[112:115], v[136:139], v[194:197], v[112:115]
	v_mfma_f32_16x16x32_bf16 v[92:95], v[128:131], v[202:205], v[92:95]
	v_mfma_f32_16x16x32_bf16 v[84:87], v[136:139], v[202:205], v[84:87]
	v_mfma_f32_16x16x32_bf16 v[88:91], v[128:131], v[210:213], v[88:91]
	v_mfma_f32_16x16x32_bf16 v[80:83], v[136:139], v[210:213], v[80:83]
	v_mfma_f32_16x16x32_bf16 v[124:127], v[132:135], v[190:193], v[124:127]
	v_mfma_f32_16x16x32_bf16 v[116:119], v[140:143], v[190:193], v[116:119]
	v_mfma_f32_16x16x32_bf16 v[120:123], v[132:135], v[198:201], v[120:123]
	v_mfma_f32_16x16x32_bf16 v[112:115], v[140:143], v[198:201], v[112:115]
	v_mfma_f32_16x16x32_bf16 v[92:95], v[132:135], v[206:209], v[92:95]
	v_mfma_f32_16x16x32_bf16 v[84:87], v[140:143], v[206:209], v[84:87]
	v_mfma_f32_16x16x32_bf16 v[88:91], v[132:135], v[214:217], v[88:91]
	v_mfma_f32_16x16x32_bf16 v[80:83], v[140:143], v[214:217], v[80:83]
	v_mfma_f32_16x16x32_bf16 v[108:111], v[218:221], v[162:165], v[108:111]
	v_mfma_f32_16x16x32_bf16 v[100:103], v[226:229], v[162:165], v[100:103]
	v_mfma_f32_16x16x32_bf16 v[104:107], v[218:221], v[194:197], v[104:107]
	v_mfma_f32_16x16x32_bf16 v[96:99], v[226:229], v[194:197], v[96:99]
	v_mfma_f32_16x16x32_bf16 v[76:79], v[218:221], v[202:205], v[76:79]
	v_mfma_f32_16x16x32_bf16 v[68:71], v[226:229], v[202:205], v[68:71]
	v_mfma_f32_16x16x32_bf16 v[72:75], v[218:221], v[210:213], v[72:75]
	v_mfma_f32_16x16x32_bf16 v[64:67], v[226:229], v[210:213], v[64:67]
	v_mfma_f32_16x16x32_bf16 v[108:111], v[222:225], v[190:193], v[108:111]
	v_mfma_f32_16x16x32_bf16 v[100:103], v[230:233], v[190:193], v[100:103]
	v_mfma_f32_16x16x32_bf16 v[104:107], v[222:225], v[198:201], v[104:107]
	v_mfma_f32_16x16x32_bf16 v[96:99], v[230:233], v[198:201], v[96:99]
	v_mfma_f32_16x16x32_bf16 v[76:79], v[222:225], v[206:209], v[76:79]
	v_mfma_f32_16x16x32_bf16 v[68:71], v[230:233], v[206:209], v[68:71]
	v_mfma_f32_16x16x32_bf16 v[72:75], v[222:225], v[214:217], v[72:75]
	v_mfma_f32_16x16x32_bf16 v[64:67], v[230:233], v[214:217], v[64:67]
	s_setprio 0
	s_barrier
	ds_read_b128 v[162:165], v188 offset:49152
	ds_read_b128 v[190:193], v188 offset:50176
	ds_read_b128 v[194:197], v188 offset:51200
	ds_read_b128 v[198:201], v188 offset:52224
	ds_read_b128 v[202:205], v188 offset:53248
	ds_read_b128 v[206:209], v188 offset:54272
	ds_read_b128 v[210:213], v188 offset:55296
	ds_read_b128 v[214:217], v188 offset:56320
	s_add_u32 s4, s78, 0x80
	s_addc_u32 s5, s79, 0
	s_add_i32 m0, s81, 0x18000
	s_nop 0
	global_load_lds_dwordx4 v154, s[4:5]
	s_add_i32 m0, s81, 0x1a000
	s_nop 0
	global_load_lds_dwordx4 v146, s[4:5]
	s_add_u32 s4, vcc_lo, 0x80
	s_addc_u32 s5, vcc_hi, 0
	s_add_i32 m0, s81, 0x8000
	s_nop 0
	global_load_lds_dwordx4 v152, s[4:5]
	s_add_i32 m0, s81, 0xa000
	s_nop 0
	global_load_lds_dwordx4 v144, s[4:5]
	s_add_u32 s4, s78, s26
	s_addc_u32 s5, s79, 0
	s_add_u32 s4, s4, 0x80
	s_addc_u32 s5, s5, 0
	s_add_i32 m0, s81, 0x1c000
	s_nop 0
	global_load_lds_dwordx4 v154, s[4:5]
	s_add_i32 m0, s81, 0x1e000
	s_nop 0
	global_load_lds_dwordx4 v146, s[4:5]
	s_waitcnt vmcnt(8)
	s_waitcnt lgkmcnt(0)
	s_barrier
	s_setprio 1
	v_mfma_f32_16x16x32_bf16 v[60:63], v[128:131], v[162:165], v[60:63]
	v_mfma_f32_16x16x32_bf16 v[56:59], v[136:139], v[162:165], v[56:59]
	v_mfma_f32_16x16x32_bf16 v[52:55], v[128:131], v[194:197], v[52:55]
	v_mfma_f32_16x16x32_bf16 v[48:51], v[136:139], v[194:197], v[48:51]
	v_mfma_f32_16x16x32_bf16 v[28:31], v[128:131], v[202:205], v[28:31]
	v_mfma_f32_16x16x32_bf16 v[20:23], v[136:139], v[202:205], v[20:23]
	v_mfma_f32_16x16x32_bf16 v[24:27], v[128:131], v[210:213], v[24:27]
	v_mfma_f32_16x16x32_bf16 v[16:19], v[136:139], v[210:213], v[16:19]
	v_mfma_f32_16x16x32_bf16 v[60:63], v[132:135], v[190:193], v[60:63]
	v_mfma_f32_16x16x32_bf16 v[56:59], v[140:143], v[190:193], v[56:59]
	v_mfma_f32_16x16x32_bf16 v[52:55], v[132:135], v[198:201], v[52:55]
	v_mfma_f32_16x16x32_bf16 v[48:51], v[140:143], v[198:201], v[48:51]
	v_mfma_f32_16x16x32_bf16 v[28:31], v[132:135], v[206:209], v[28:31]
	v_mfma_f32_16x16x32_bf16 v[20:23], v[140:143], v[206:209], v[20:23]
	v_mfma_f32_16x16x32_bf16 v[24:27], v[132:135], v[214:217], v[24:27]
	v_mfma_f32_16x16x32_bf16 v[16:19], v[140:143], v[214:217], v[16:19]
	v_mfma_f32_16x16x32_bf16 v[44:47], v[218:221], v[162:165], v[44:47]
	v_mfma_f32_16x16x32_bf16 v[36:39], v[226:229], v[162:165], v[36:39]
	v_mfma_f32_16x16x32_bf16 v[40:43], v[218:221], v[194:197], v[40:43]
	v_mfma_f32_16x16x32_bf16 v[32:35], v[226:229], v[194:197], v[32:35]
	v_mfma_f32_16x16x32_bf16 v[12:15], v[218:221], v[202:205], v[12:15]
	v_mfma_f32_16x16x32_bf16 v[4:7], v[226:229], v[202:205], v[4:7]
	v_mfma_f32_16x16x32_bf16 v[8:11], v[218:221], v[210:213], v[8:11]
	v_mfma_f32_16x16x32_bf16 v[0:3], v[226:229], v[210:213], v[0:3]
	v_mfma_f32_16x16x32_bf16 v[44:47], v[222:225], v[190:193], v[44:47]
	v_mfma_f32_16x16x32_bf16 v[36:39], v[230:233], v[190:193], v[36:39]
	v_mfma_f32_16x16x32_bf16 v[40:43], v[222:225], v[198:201], v[40:43]
	v_mfma_f32_16x16x32_bf16 v[32:35], v[230:233], v[198:201], v[32:35]
	v_mfma_f32_16x16x32_bf16 v[12:15], v[222:225], v[206:209], v[12:15]
	v_mfma_f32_16x16x32_bf16 v[4:7], v[230:233], v[206:209], v[4:7]
	v_mfma_f32_16x16x32_bf16 v[8:11], v[222:225], v[214:217], v[8:11]
	v_mfma_f32_16x16x32_bf16 v[0:3], v[230:233], v[214:217], v[0:3]
	s_setprio 0
	s_add_u32 s10, s10, 0x100
	s_addc_u32 s11, s11, 0
	s_add_u32 s84, s84, 0x100
	s_addc_u32 s85, s85, 0
	s_cmp_ge_u32 s72, s76
	s_mov_b32 s78, s72
	s_barrier
	s_cbranch_scc0 .LBB0_522
	v_lshl_add_u32 v162, s20, 8, v151
	s_cmp_lt_i32 s45, 2
	s_mov_b64 s[10:11], -1
	s_cbranch_scc1 .LBB0_537
	s_cmp_gt_i32 s45, 2
	s_cbranch_scc0 .LBB0_534
	s_add_i32 s10, s25, 2
	s_cmp_gt_u32 s10, 4
	s_mov_b64 s[10:11], -1
	s_cbranch_scc0 .LBB0_531
	s_add_i32 s10, s25, -3
	s_cmp_gt_u32 s10, 2
	v_lshl_or_b32 v148, s25, 8, v186
	s_mov_b64 s[10:11], -1
	s_cbranch_scc0 .LBB0_528
	v_ashrrev_i32_e32 v128, 31, v162
	v_mul_lo_u32 v134, s29, v162
	v_mul_lo_u32 v136, s28, v128
	v_mad_u64_u32 v[128:129], s[10:11], s28, v162, 0
	v_add3_u32 v129, v129, v136, v134
	v_lshl_add_u64 v[134:135], v[128:129], 1, s[70:71]
	v_ashrrev_i32_e32 v129, 31, v148
	v_mov_b32_e32 v128, v148
	v_lshlrev_b64 v[128:129], 1, v[128:129]
	v_cvt_pk_bf16_f32 v130, v124, v125
	v_cvt_pk_bf16_f32 v131, v126, v127
	v_cvt_pk_bf16_f32 v132, v116, v117
	v_cvt_pk_bf16_f32 v133, v118, v119
	v_lshl_add_u64 v[134:135], v[134:135], 0, v[128:129]
	global_store_dwordx4 v[134:135], v[130:133], off nt
	s_nop 1
	v_cvt_pk_bf16_f32 v130, v108, v109
	v_cvt_pk_bf16_f32 v131, v110, v111
	v_cvt_pk_bf16_f32 v132, v100, v101
	v_cvt_pk_bf16_f32 v133, v102, v103
	global_store_dwordx4 v[134:135], v[130:133], off offset:256 nt
	v_or_b32_e32 v134, 16, v162
	v_mul_lo_u32 v137, s29, v134
	v_mad_u64_u32 v[134:135], s[10:11], s28, v134, 0
	v_add3_u32 v135, v135, v136, v137
	v_lshl_add_u64 v[134:135], v[134:135], 1, s[70:71]
	v_cvt_pk_bf16_f32 v130, v120, v121
	v_cvt_pk_bf16_f32 v131, v122, v123
	v_cvt_pk_bf16_f32 v132, v112, v113
	v_cvt_pk_bf16_f32 v133, v114, v115
	v_lshl_add_u64 v[134:135], v[134:135], 0, v[128:129]
	global_store_dwordx4 v[134:135], v[130:133], off nt
	s_nop 1
	v_cvt_pk_bf16_f32 v130, v104, v105
	v_cvt_pk_bf16_f32 v131, v106, v107
	v_cvt_pk_bf16_f32 v132, v96, v97
	v_cvt_pk_bf16_f32 v133, v98, v99
	global_store_dwordx4 v[134:135], v[130:133], off offset:256 nt
	v_or_b32_e32 v134, 32, v162
	v_mul_lo_u32 v137, s29, v134
	v_mad_u64_u32 v[134:135], s[10:11], s28, v134, 0
	v_add3_u32 v135, v135, v136, v137
	v_lshl_add_u64 v[134:135], v[134:135], 1, s[70:71]
	v_cvt_pk_bf16_f32 v130, v92, v93
	v_cvt_pk_bf16_f32 v131, v94, v95
	v_cvt_pk_bf16_f32 v132, v84, v85
	v_cvt_pk_bf16_f32 v133, v86, v87
	v_lshl_add_u64 v[134:135], v[134:135], 0, v[128:129]
	global_store_dwordx4 v[134:135], v[130:133], off nt
	s_nop 1
	v_cvt_pk_bf16_f32 v130, v76, v77
	v_cvt_pk_bf16_f32 v131, v78, v79
	v_cvt_pk_bf16_f32 v132, v68, v69
	v_cvt_pk_bf16_f32 v133, v70, v71
	global_store_dwordx4 v[134:135], v[130:133], off offset:256 nt
	v_or_b32_e32 v134, 48, v162
	v_mul_lo_u32 v137, s29, v134
	v_mad_u64_u32 v[134:135], s[10:11], s28, v134, 0
	v_add3_u32 v135, v135, v136, v137
	v_lshl_add_u64 v[134:135], v[134:135], 1, s[70:71]
	v_cvt_pk_bf16_f32 v130, v88, v89
	v_cvt_pk_bf16_f32 v131, v90, v91
	v_cvt_pk_bf16_f32 v132, v80, v81
	v_cvt_pk_bf16_f32 v133, v82, v83
	v_lshl_add_u64 v[134:135], v[134:135], 0, v[128:129]
	global_store_dwordx4 v[134:135], v[130:133], off nt
	s_nop 1
	v_cvt_pk_bf16_f32 v130, v72, v73
	v_cvt_pk_bf16_f32 v131, v74, v75
	v_cvt_pk_bf16_f32 v132, v64, v65
	v_cvt_pk_bf16_f32 v133, v66, v67
	global_store_dwordx4 v[134:135], v[130:133], off offset:256 nt
	v_add_u32_e32 v134, 0x80, v162
	v_ashrrev_i32_e32 v135, 31, v134
	v_mul_lo_u32 v136, s28, v135
	v_mul_lo_u32 v137, s29, v134
	v_mad_u64_u32 v[134:135], s[10:11], s28, v134, 0
	v_add3_u32 v135, v135, v136, v137
	v_lshl_add_u64 v[134:135], v[134:135], 1, s[70:71]
	v_cvt_pk_bf16_f32 v130, v60, v61
	v_cvt_pk_bf16_f32 v131, v62, v63
	v_cvt_pk_bf16_f32 v132, v56, v57
	v_cvt_pk_bf16_f32 v133, v58, v59
	v_lshl_add_u64 v[134:135], v[134:135], 0, v[128:129]
	global_store_dwordx4 v[134:135], v[130:133], off nt
	s_nop 1
	v_cvt_pk_bf16_f32 v130, v44, v45
	v_cvt_pk_bf16_f32 v131, v46, v47
	v_cvt_pk_bf16_f32 v132, v36, v37
	v_cvt_pk_bf16_f32 v133, v38, v39
	global_store_dwordx4 v[134:135], v[130:133], off offset:256 nt
	v_add_u32_e32 v134, 0x90, v162
	v_ashrrev_i32_e32 v135, 31, v134
	v_mul_lo_u32 v136, s28, v135
	v_mul_lo_u32 v137, s29, v134
	v_mad_u64_u32 v[134:135], s[10:11], s28, v134, 0
	v_add3_u32 v135, v135, v136, v137
	v_lshl_add_u64 v[134:135], v[134:135], 1, s[70:71]
	v_cvt_pk_bf16_f32 v130, v52, v53
	v_cvt_pk_bf16_f32 v131, v54, v55
	v_cvt_pk_bf16_f32 v132, v48, v49
	v_cvt_pk_bf16_f32 v133, v50, v51
	v_lshl_add_u64 v[134:135], v[134:135], 0, v[128:129]
	global_store_dwordx4 v[134:135], v[130:133], off nt
	s_nop 1
	v_cvt_pk_bf16_f32 v130, v40, v41
	v_cvt_pk_bf16_f32 v131, v42, v43
	v_cvt_pk_bf16_f32 v132, v32, v33
	v_cvt_pk_bf16_f32 v133, v34, v35
	global_store_dwordx4 v[134:135], v[130:133], off offset:256 nt
	v_add_u32_e32 v134, 0xa0, v162
	v_ashrrev_i32_e32 v135, 31, v134
	v_mul_lo_u32 v136, s28, v135
	v_mul_lo_u32 v137, s29, v134
	v_mad_u64_u32 v[134:135], s[10:11], s28, v134, 0
	v_add3_u32 v135, v135, v136, v137
	v_lshl_add_u64 v[134:135], v[134:135], 1, s[70:71]
	v_cvt_pk_bf16_f32 v130, v28, v29
	v_cvt_pk_bf16_f32 v131, v30, v31
	v_cvt_pk_bf16_f32 v132, v20, v21
	v_cvt_pk_bf16_f32 v133, v22, v23
	v_lshl_add_u64 v[134:135], v[134:135], 0, v[128:129]
	global_store_dwordx4 v[134:135], v[130:133], off nt
	s_nop 1
	v_cvt_pk_bf16_f32 v130, v12, v13
	v_cvt_pk_bf16_f32 v131, v14, v15
	v_cvt_pk_bf16_f32 v132, v4, v5
	v_cvt_pk_bf16_f32 v133, v6, v7
	global_store_dwordx4 v[134:135], v[130:133], off offset:256 nt
	v_add_u32_e32 v134, 0xb0, v162
	v_ashrrev_i32_e32 v135, 31, v134
	v_mul_lo_u32 v136, s28, v135
	v_mul_lo_u32 v137, s29, v134
	v_mad_u64_u32 v[134:135], s[10:11], s28, v134, 0
	v_add3_u32 v135, v135, v136, v137
	v_lshl_add_u64 v[134:135], v[134:135], 1, s[70:71]
	v_cvt_pk_bf16_f32 v130, v24, v25
	v_cvt_pk_bf16_f32 v131, v26, v27
	v_lshl_add_u64 v[134:135], v[134:135], 0, v[128:129]
	v_cvt_pk_bf16_f32 v132, v16, v17
	v_cvt_pk_bf16_f32 v133, v18, v19
	global_store_dwordx4 v[134:135], v[130:133], off nt
	v_cvt_pk_bf16_f32 v128, v8, v9
	v_cvt_pk_bf16_f32 v129, v10, v11
	s_mov_b64 s[10:11], 0
	s_nop 0
	v_cvt_pk_bf16_f32 v130, v0, v1
	v_cvt_pk_bf16_f32 v131, v2, v3
	global_store_dwordx4 v[134:135], v[128:131], off offset:256 nt
.LBB0_528:
	s_andn2_b64 vcc, exec, s[10:11]
	s_cbranch_vccnz .LBB0_530
	s_movk_i32 s10, 0xf400
	v_lshl_add_u64 v[132:133], v[148:149], 2, s[40:41]
	s_mov_b32 s11, -1
	v_lshl_add_u64 v[164:165], v[132:133], 0, s[10:11]
	global_load_dwordx4 v[136:139], v[132:133], off offset:-3056
	global_load_dwordx4 v[140:143], v[132:133], off offset:-3072
	global_load_dwordx4 v[128:131], v[132:133], off offset:-2544
	s_nop 0
	global_load_dwordx4 v[132:135], v[132:133], off offset:-2560
	v_ashrrev_i32_e32 v163, 31, v162
	v_mul_lo_u32 v163, s28, v163
	s_waitcnt vmcnt(0)
	v_add_f32_e32 v173, v116, v136
	v_add_f32_e32 v164, v124, v140
	v_add_f32_e32 v165, v125, v141
	v_add_f32_e32 v166, v126, v142
	v_mul_f32_e32 v164, 0xbfb8aa3b, v164
	v_mul_f32_e32 v165, 0xbfb8aa3b, v165
	v_mul_f32_e32 v166, 0xbfb8aa3b, v166
	v_add_f32_e32 v167, v127, v143
	v_exp_f32_e32 v164, v164
	v_exp_f32_e32 v165, v165
	v_exp_f32_e32 v166, v166
	v_mul_f32_e32 v167, 0xbfb8aa3b, v167
	v_mul_f32_e32 v173, 0xbfb8aa3b, v173
	v_add_f32_e32 v174, v117, v137
	v_add_f32_e32 v175, v118, v138
	v_add_f32_e32 v177, v119, v139
	v_exp_f32_e32 v167, v167
	v_exp_f32_e32 v173, v173
	v_mul_f32_e32 v174, 0xbfb8aa3b, v174
	v_mul_f32_e32 v175, 0xbfb8aa3b, v175
	v_mul_f32_e32 v177, 0xbfb8aa3b, v177
	v_exp_f32_e32 v174, v174
	v_exp_f32_e32 v175, v175
	v_exp_f32_e32 v177, v177
	v_add_f32_e32 v164, 1.0, v164
	v_add_f32_e32 v165, 1.0, v165
	v_add_f32_e32 v166, 1.0, v166
	v_rcp_f32_e32 v164, v164
	v_rcp_f32_e32 v165, v165
	v_rcp_f32_e32 v166, v166
	v_add_f32_e32 v167, 1.0, v167
	v_add_f32_e32 v173, 1.0, v173
	v_rcp_f32_e32 v167, v167
	v_rcp_f32_e32 v173, v173
	v_add_f32_e32 v174, 1.0, v174
	v_add_f32_e32 v175, 1.0, v175
	v_add_f32_e32 v177, 1.0, v177
	v_cvt_pk_bf16_f32 v190, v164, v165
	v_cvt_pk_bf16_f32 v191, v166, v167
	v_mul_lo_u32 v166, s29, v162
	v_mad_u64_u32 v[164:165], s[10:11], s28, v162, 0
	v_rcp_f32_e32 v174, v174
	v_rcp_f32_e32 v175, v175
	v_rcp_f32_e32 v177, v177
	v_cvt_pk_bf16_f32 v192, v173, v174
	v_add3_u32 v165, v165, v163, v166
	v_add_f32_e32 v173, v109, v133
	v_cvt_pk_bf16_f32 v193, v175, v177
	v_lshl_add_u64 v[166:167], v[164:165], 1, s[70:71]
	v_lshlrev_b64 v[164:165], 1, v[148:149]
	v_add_f32_e32 v148, v108, v132
	v_mul_f32_e32 v173, 0xbfb8aa3b, v173
	v_add_f32_e32 v174, v110, v134
	v_add_f32_e32 v175, v111, v135
	v_add_f32_e32 v177, v100, v128
	v_add_f32_e32 v181, v101, v129
	v_add_f32_e32 v183, v102, v130
	v_add_f32_e32 v184, v103, v131
	v_mul_f32_e32 v148, 0xbfb8aa3b, v148
	v_exp_f32_e32 v173, v173
	v_mul_f32_e32 v174, 0xbfb8aa3b, v174
	v_mul_f32_e32 v175, 0xbfb8aa3b, v175
	v_mul_f32_e32 v177, 0xbfb8aa3b, v177
	v_mul_f32_e32 v181, 0xbfb8aa3b, v181
	v_mul_f32_e32 v183, 0xbfb8aa3b, v183
	v_mul_f32_e32 v184, 0xbfb8aa3b, v184
	v_exp_f32_e32 v148, v148
	v_exp_f32_e32 v174, v174
	v_exp_f32_e32 v175, v175
	v_exp_f32_e32 v177, v177
	v_exp_f32_e32 v181, v181
	v_exp_f32_e32 v183, v183
	v_exp_f32_e32 v184, v184
	v_add_f32_e32 v173, 1.0, v173
	v_lshl_add_u64 v[166:167], v[166:167], 0, v[164:165]
	v_add_f32_e32 v148, 1.0, v148
	v_rcp_f32_e32 v173, v173
	v_add_f32_e32 v174, 1.0, v174
	v_add_f32_e32 v175, 1.0, v175
	v_add_f32_e32 v177, 1.0, v177
	v_add_f32_e32 v181, 1.0, v181
	v_add_f32_e32 v183, 1.0, v183
	v_add_f32_e32 v184, 1.0, v184
	global_store_dwordx4 v[166:167], v[190:193], off nt
	v_rcp_f32_e32 v148, v148
	v_rcp_f32_e32 v174, v174
	v_rcp_f32_e32 v175, v175
	v_rcp_f32_e32 v177, v177
	v_rcp_f32_e32 v181, v181
	v_rcp_f32_e32 v183, v183
	v_rcp_f32_e32 v184, v184
	v_cvt_pk_bf16_f32 v190, v148, v173
	v_cvt_pk_bf16_f32 v191, v174, v175
	v_cvt_pk_bf16_f32 v192, v177, v181
	v_cvt_pk_bf16_f32 v193, v183, v184
	global_store_dwordx4 v[166:167], v[190:193], off offset:256 nt
	v_add_f32_e32 v166, v120, v140
	v_add_f32_e32 v167, v121, v141
	v_add_f32_e32 v173, v122, v142
	v_mul_f32_e32 v166, 0xbfb8aa3b, v166
	v_mul_f32_e32 v167, 0xbfb8aa3b, v167
	v_mul_f32_e32 v173, 0xbfb8aa3b, v173
	v_add_f32_e32 v174, v123, v143
	v_exp_f32_e32 v166, v166
	v_exp_f32_e32 v167, v167
	v_exp_f32_e32 v173, v173
	v_mul_f32_e32 v174, 0xbfb8aa3b, v174
	v_add_f32_e32 v175, v112, v136
	v_add_f32_e32 v177, v113, v137
	v_add_f32_e32 v181, v114, v138
	v_add_f32_e32 v183, v115, v139
	v_exp_f32_e32 v174, v174
	v_mul_f32_e32 v175, 0xbfb8aa3b, v175
	v_mul_f32_e32 v177, 0xbfb8aa3b, v177
	v_mul_f32_e32 v181, 0xbfb8aa3b, v181
	v_mul_f32_e32 v183, 0xbfb8aa3b, v183
	v_exp_f32_e32 v175, v175
	v_exp_f32_e32 v177, v177
	v_exp_f32_e32 v181, v181
	v_exp_f32_e32 v183, v183
	v_add_f32_e32 v166, 1.0, v166
	v_add_f32_e32 v167, 1.0, v167
	v_add_f32_e32 v173, 1.0, v173
	v_or_b32_e32 v148, 16, v162
	v_rcp_f32_e32 v166, v166
	v_rcp_f32_e32 v167, v167
	v_rcp_f32_e32 v173, v173
	v_add_f32_e32 v174, 1.0, v174
	v_rcp_f32_e32 v174, v174
	v_add_f32_e32 v175, 1.0, v175
	v_add_f32_e32 v177, 1.0, v177
	v_add_f32_e32 v181, 1.0, v181
	v_add_f32_e32 v183, 1.0, v183
	v_cvt_pk_bf16_f32 v190, v166, v167
	v_cvt_pk_bf16_f32 v191, v173, v174
	v_mul_lo_u32 v173, s29, v148
	v_mad_u64_u32 v[166:167], s[10:11], s28, v148, 0
	v_rcp_f32_e32 v175, v175
	v_rcp_f32_e32 v177, v177
	v_rcp_f32_e32 v181, v181
	v_rcp_f32_e32 v183, v183
	v_add3_u32 v167, v167, v163, v173
	v_add_f32_e32 v173, v105, v133
	v_cvt_pk_bf16_f32 v192, v175, v177
	v_cvt_pk_bf16_f32 v193, v181, v183
	v_add_f32_e32 v148, v104, v132
	v_mul_f32_e32 v173, 0xbfb8aa3b, v173
	v_add_f32_e32 v174, v106, v134
	v_add_f32_e32 v175, v107, v135
	v_add_f32_e32 v177, v96, v128
	v_add_f32_e32 v181, v97, v129
	v_add_f32_e32 v183, v98, v130
	v_add_f32_e32 v184, v99, v131
	v_mul_f32_e32 v148, 0xbfb8aa3b, v148
	v_exp_f32_e32 v173, v173
	v_mul_f32_e32 v174, 0xbfb8aa3b, v174
	v_mul_f32_e32 v175, 0xbfb8aa3b, v175
	v_mul_f32_e32 v177, 0xbfb8aa3b, v177
	v_mul_f32_e32 v181, 0xbfb8aa3b, v181
	v_mul_f32_e32 v183, 0xbfb8aa3b, v183
	v_mul_f32_e32 v184, 0xbfb8aa3b, v184
	v_exp_f32_e32 v148, v148
	v_exp_f32_e32 v174, v174
	v_exp_f32_e32 v175, v175
	v_exp_f32_e32 v177, v177
	v_exp_f32_e32 v181, v181
	v_exp_f32_e32 v183, v183
	v_exp_f32_e32 v184, v184
	v_lshl_add_u64 v[166:167], v[166:167], 1, s[70:71]
	v_add_f32_e32 v173, 1.0, v173
	v_lshl_add_u64 v[166:167], v[166:167], 0, v[164:165]
	v_add_f32_e32 v148, 1.0, v148
	v_rcp_f32_e32 v173, v173
	v_add_f32_e32 v174, 1.0, v174
	v_add_f32_e32 v175, 1.0, v175
	v_add_f32_e32 v177, 1.0, v177
	v_add_f32_e32 v181, 1.0, v181
	v_add_f32_e32 v183, 1.0, v183
	v_add_f32_e32 v184, 1.0, v184
	global_store_dwordx4 v[166:167], v[190:193], off nt
	v_rcp_f32_e32 v148, v148
	v_rcp_f32_e32 v174, v174
	v_rcp_f32_e32 v175, v175
	v_rcp_f32_e32 v177, v177
	v_rcp_f32_e32 v181, v181
	v_rcp_f32_e32 v183, v183
	v_rcp_f32_e32 v184, v184
	v_cvt_pk_bf16_f32 v190, v148, v173
	v_cvt_pk_bf16_f32 v191, v174, v175
	v_cvt_pk_bf16_f32 v192, v177, v181
	v_cvt_pk_bf16_f32 v193, v183, v184
	global_store_dwordx4 v[166:167], v[190:193], off offset:256 nt
	v_add_f32_e32 v166, v92, v140
	v_add_f32_e32 v167, v93, v141
	v_add_f32_e32 v173, v94, v142
	v_mul_f32_e32 v166, 0xbfb8aa3b, v166
	v_mul_f32_e32 v167, 0xbfb8aa3b, v167
	v_mul_f32_e32 v173, 0xbfb8aa3b, v173
	v_add_f32_e32 v174, v95, v143
	v_exp_f32_e32 v166, v166
	v_exp_f32_e32 v167, v167
	v_exp_f32_e32 v173, v173
	v_mul_f32_e32 v174, 0xbfb8aa3b, v174
	v_add_f32_e32 v175, v84, v136
	v_add_f32_e32 v177, v85, v137
	v_add_f32_e32 v181, v86, v138
	v_add_f32_e32 v183, v87, v139
	v_exp_f32_e32 v174, v174
	v_mul_f32_e32 v175, 0xbfb8aa3b, v175
	v_mul_f32_e32 v177, 0xbfb8aa3b, v177
	v_mul_f32_e32 v181, 0xbfb8aa3b, v181
	v_mul_f32_e32 v183, 0xbfb8aa3b, v183
	v_exp_f32_e32 v175, v175
	v_exp_f32_e32 v177, v177
	v_exp_f32_e32 v181, v181
	v_exp_f32_e32 v183, v183
	v_add_f32_e32 v166, 1.0, v166
	v_add_f32_e32 v167, 1.0, v167
	v_add_f32_e32 v173, 1.0, v173
	v_or_b32_e32 v148, 32, v162
	v_rcp_f32_e32 v166, v166
	v_rcp_f32_e32 v167, v167
	v_rcp_f32_e32 v173, v173
	v_add_f32_e32 v174, 1.0, v174
	v_rcp_f32_e32 v174, v174
	v_add_f32_e32 v175, 1.0, v175
	v_add_f32_e32 v177, 1.0, v177
	v_add_f32_e32 v181, 1.0, v181
	v_add_f32_e32 v183, 1.0, v183
	v_cvt_pk_bf16_f32 v190, v166, v167
	v_cvt_pk_bf16_f32 v191, v173, v174
	v_mul_lo_u32 v173, s29, v148
	v_mad_u64_u32 v[166:167], s[10:11], s28, v148, 0
	v_rcp_f32_e32 v175, v175
	v_rcp_f32_e32 v177, v177
	v_rcp_f32_e32 v181, v181
	v_rcp_f32_e32 v183, v183
	v_add3_u32 v167, v167, v163, v173
	v_add_f32_e32 v173, v77, v133
	v_cvt_pk_bf16_f32 v192, v175, v177
	v_cvt_pk_bf16_f32 v193, v181, v183
	v_add_f32_e32 v148, v76, v132
	v_mul_f32_e32 v173, 0xbfb8aa3b, v173
	v_add_f32_e32 v174, v78, v134
	v_add_f32_e32 v175, v79, v135
	v_add_f32_e32 v177, v68, v128
	v_add_f32_e32 v181, v69, v129
	v_add_f32_e32 v183, v70, v130
	v_add_f32_e32 v184, v71, v131
	v_mul_f32_e32 v148, 0xbfb8aa3b, v148
	v_exp_f32_e32 v173, v173
	v_mul_f32_e32 v174, 0xbfb8aa3b, v174
	v_mul_f32_e32 v175, 0xbfb8aa3b, v175
	v_mul_f32_e32 v177, 0xbfb8aa3b, v177
	v_mul_f32_e32 v181, 0xbfb8aa3b, v181
	v_mul_f32_e32 v183, 0xbfb8aa3b, v183
	v_mul_f32_e32 v184, 0xbfb8aa3b, v184
	v_exp_f32_e32 v148, v148
	v_exp_f32_e32 v174, v174
	v_exp_f32_e32 v175, v175
	v_exp_f32_e32 v177, v177
	v_exp_f32_e32 v181, v181
	v_exp_f32_e32 v183, v183
	v_exp_f32_e32 v184, v184
	v_lshl_add_u64 v[166:167], v[166:167], 1, s[70:71]
	v_add_f32_e32 v173, 1.0, v173
	v_lshl_add_u64 v[166:167], v[166:167], 0, v[164:165]
	v_add_f32_e32 v148, 1.0, v148
	v_rcp_f32_e32 v173, v173
	v_add_f32_e32 v174, 1.0, v174
	v_add_f32_e32 v175, 1.0, v175
	v_add_f32_e32 v177, 1.0, v177
	v_add_f32_e32 v181, 1.0, v181
	v_add_f32_e32 v183, 1.0, v183
	v_add_f32_e32 v184, 1.0, v184
	global_store_dwordx4 v[166:167], v[190:193], off nt
	v_rcp_f32_e32 v148, v148
	v_rcp_f32_e32 v174, v174
	v_rcp_f32_e32 v175, v175
	v_rcp_f32_e32 v177, v177
	v_rcp_f32_e32 v181, v181
	v_rcp_f32_e32 v183, v183
	v_rcp_f32_e32 v184, v184
	v_cvt_pk_bf16_f32 v190, v148, v173
	v_cvt_pk_bf16_f32 v191, v174, v175
	v_cvt_pk_bf16_f32 v192, v177, v181
	v_cvt_pk_bf16_f32 v193, v183, v184
	global_store_dwordx4 v[166:167], v[190:193], off offset:256 nt
	v_add_f32_e32 v166, v88, v140
	v_add_f32_e32 v167, v89, v141
	v_add_f32_e32 v173, v90, v142
	v_mul_f32_e32 v166, 0xbfb8aa3b, v166
	v_mul_f32_e32 v167, 0xbfb8aa3b, v167
	v_mul_f32_e32 v173, 0xbfb8aa3b, v173
	v_add_f32_e32 v174, v91, v143
	v_exp_f32_e32 v166, v166
	v_exp_f32_e32 v167, v167
	v_exp_f32_e32 v173, v173
	v_mul_f32_e32 v174, 0xbfb8aa3b, v174
	v_add_f32_e32 v175, v80, v136
	v_add_f32_e32 v177, v81, v137
	v_add_f32_e32 v181, v82, v138
	v_add_f32_e32 v183, v83, v139
	v_exp_f32_e32 v174, v174
	v_mul_f32_e32 v175, 0xbfb8aa3b, v175
	v_mul_f32_e32 v177, 0xbfb8aa3b, v177
	v_mul_f32_e32 v181, 0xbfb8aa3b, v181
	v_mul_f32_e32 v183, 0xbfb8aa3b, v183
	v_exp_f32_e32 v175, v175
	v_exp_f32_e32 v177, v177
	v_exp_f32_e32 v181, v181
	v_exp_f32_e32 v183, v183
	v_add_f32_e32 v166, 1.0, v166
	v_add_f32_e32 v167, 1.0, v167
	v_add_f32_e32 v173, 1.0, v173
	v_or_b32_e32 v148, 48, v162
	v_rcp_f32_e32 v166, v166
	v_rcp_f32_e32 v167, v167
	v_rcp_f32_e32 v173, v173
	v_add_f32_e32 v174, 1.0, v174
	v_rcp_f32_e32 v174, v174
	v_add_f32_e32 v175, 1.0, v175
	v_add_f32_e32 v177, 1.0, v177
	v_add_f32_e32 v181, 1.0, v181
	v_add_f32_e32 v183, 1.0, v183
	v_cvt_pk_bf16_f32 v190, v166, v167
	v_cvt_pk_bf16_f32 v191, v173, v174
	v_mul_lo_u32 v173, s29, v148
	v_mad_u64_u32 v[166:167], s[10:11], s28, v148, 0
	v_rcp_f32_e32 v175, v175
	v_rcp_f32_e32 v177, v177
	v_rcp_f32_e32 v181, v181
	v_rcp_f32_e32 v183, v183
	v_add3_u32 v167, v167, v163, v173
	v_add_f32_e32 v173, v74, v134
	v_cvt_pk_bf16_f32 v192, v175, v177
	v_cvt_pk_bf16_f32 v193, v181, v183
	v_add_f32_e32 v148, v72, v132
	v_add_f32_e32 v163, v73, v133
	v_mul_f32_e32 v173, 0xbfb8aa3b, v173
	v_add_f32_e32 v174, v75, v135
	v_add_f32_e32 v175, v64, v128
	v_add_f32_e32 v177, v65, v129
	v_add_f32_e32 v181, v66, v130
	v_add_f32_e32 v183, v67, v131
	v_mul_f32_e32 v148, 0xbfb8aa3b, v148
	v_mul_f32_e32 v163, 0xbfb8aa3b, v163
	v_exp_f32_e32 v173, v173
	v_mul_f32_e32 v174, 0xbfb8aa3b, v174
	v_mul_f32_e32 v175, 0xbfb8aa3b, v175
	v_mul_f32_e32 v177, 0xbfb8aa3b, v177
	v_mul_f32_e32 v181, 0xbfb8aa3b, v181
	v_mul_f32_e32 v183, 0xbfb8aa3b, v183
	v_exp_f32_e32 v148, v148
	v_exp_f32_e32 v163, v163
	v_exp_f32_e32 v174, v174
	v_exp_f32_e32 v175, v175
	v_exp_f32_e32 v177, v177
	v_exp_f32_e32 v181, v181
	v_exp_f32_e32 v183, v183
	v_lshl_add_u64 v[166:167], v[166:167], 1, s[70:71]
	v_add_f32_e32 v173, 1.0, v173
	v_lshl_add_u64 v[166:167], v[166:167], 0, v[164:165]
	v_add_f32_e32 v148, 1.0, v148
	v_add_f32_e32 v163, 1.0, v163
	v_rcp_f32_e32 v173, v173
	v_add_f32_e32 v174, 1.0, v174
	v_add_f32_e32 v175, 1.0, v175
	v_add_f32_e32 v177, 1.0, v177
	v_add_f32_e32 v181, 1.0, v181
	v_add_f32_e32 v183, 1.0, v183
	global_store_dwordx4 v[166:167], v[190:193], off nt
	v_rcp_f32_e32 v148, v148
	v_rcp_f32_e32 v163, v163
	v_rcp_f32_e32 v174, v174
	v_rcp_f32_e32 v175, v175
	v_rcp_f32_e32 v177, v177
	v_rcp_f32_e32 v181, v181
	v_rcp_f32_e32 v183, v183
	v_cvt_pk_bf16_f32 v190, v148, v163
	v_cvt_pk_bf16_f32 v191, v173, v174
	v_cvt_pk_bf16_f32 v192, v175, v177
	v_cvt_pk_bf16_f32 v193, v181, v183
	global_store_dwordx4 v[166:167], v[190:193], off offset:256 nt
	v_add_f32_e32 v166, v60, v140
	v_add_f32_e32 v167, v61, v141
	v_add_f32_e32 v173, v62, v142
	v_mul_f32_e32 v166, 0xbfb8aa3b, v166
	v_mul_f32_e32 v167, 0xbfb8aa3b, v167
	v_mul_f32_e32 v173, 0xbfb8aa3b, v173
	v_add_f32_e32 v174, v63, v143
	v_exp_f32_e32 v166, v166
	v_exp_f32_e32 v167, v167
	v_exp_f32_e32 v173, v173
	v_mul_f32_e32 v174, 0xbfb8aa3b, v174
	v_add_f32_e32 v175, v56, v136
	v_add_f32_e32 v177, v57, v137
	v_add_f32_e32 v181, v58, v138
	v_add_f32_e32 v183, v59, v139
	v_exp_f32_e32 v174, v174
	v_mul_f32_e32 v175, 0xbfb8aa3b, v175
	v_mul_f32_e32 v177, 0xbfb8aa3b, v177
	v_mul_f32_e32 v181, 0xbfb8aa3b, v181
	v_mul_f32_e32 v183, 0xbfb8aa3b, v183
	v_exp_f32_e32 v175, v175
	v_exp_f32_e32 v177, v177
	v_exp_f32_e32 v181, v181
	v_exp_f32_e32 v183, v183
	v_add_u32_e32 v148, 0x80, v162
	v_add_f32_e32 v166, 1.0, v166
	v_add_f32_e32 v167, 1.0, v167
	v_add_f32_e32 v173, 1.0, v173
	v_ashrrev_i32_e32 v163, 31, v148
	v_rcp_f32_e32 v166, v166
	v_rcp_f32_e32 v167, v167
	v_rcp_f32_e32 v173, v173
	v_add_f32_e32 v174, 1.0, v174
	v_rcp_f32_e32 v174, v174
	v_add_f32_e32 v175, 1.0, v175
	v_add_f32_e32 v177, 1.0, v177
	v_add_f32_e32 v181, 1.0, v181
	v_add_f32_e32 v183, 1.0, v183
	v_cvt_pk_bf16_f32 v190, v166, v167
	v_cvt_pk_bf16_f32 v191, v173, v174
	v_mul_lo_u32 v163, s28, v163
	v_mul_lo_u32 v173, s29, v148
	v_mad_u64_u32 v[166:167], s[10:11], s28, v148, 0
	v_rcp_f32_e32 v175, v175
	v_rcp_f32_e32 v177, v177
	v_rcp_f32_e32 v181, v181
	v_rcp_f32_e32 v183, v183
	v_add3_u32 v167, v167, v163, v173
	v_add_f32_e32 v173, v46, v134
	v_cvt_pk_bf16_f32 v192, v175, v177
	v_cvt_pk_bf16_f32 v193, v181, v183
	v_add_f32_e32 v148, v44, v132
	v_add_f32_e32 v163, v45, v133
	v_mul_f32_e32 v173, 0xbfb8aa3b, v173
	v_add_f32_e32 v174, v47, v135
	v_add_f32_e32 v175, v36, v128
	v_add_f32_e32 v177, v37, v129
	v_add_f32_e32 v181, v38, v130
	v_add_f32_e32 v183, v39, v131
	v_mul_f32_e32 v148, 0xbfb8aa3b, v148
	v_mul_f32_e32 v163, 0xbfb8aa3b, v163
	v_exp_f32_e32 v173, v173
	v_mul_f32_e32 v174, 0xbfb8aa3b, v174
	v_mul_f32_e32 v175, 0xbfb8aa3b, v175
	v_mul_f32_e32 v177, 0xbfb8aa3b, v177
	v_mul_f32_e32 v181, 0xbfb8aa3b, v181
	v_mul_f32_e32 v183, 0xbfb8aa3b, v183
	v_exp_f32_e32 v148, v148
	v_exp_f32_e32 v163, v163
	v_exp_f32_e32 v174, v174
	v_exp_f32_e32 v175, v175
	v_exp_f32_e32 v177, v177
	v_exp_f32_e32 v181, v181
	v_exp_f32_e32 v183, v183
	v_lshl_add_u64 v[166:167], v[166:167], 1, s[70:71]
	v_add_f32_e32 v173, 1.0, v173
	v_lshl_add_u64 v[166:167], v[166:167], 0, v[164:165]
	v_add_f32_e32 v148, 1.0, v148
	v_add_f32_e32 v163, 1.0, v163
	v_rcp_f32_e32 v173, v173
	v_add_f32_e32 v174, 1.0, v174
	v_add_f32_e32 v175, 1.0, v175
	v_add_f32_e32 v177, 1.0, v177
	v_add_f32_e32 v181, 1.0, v181
	v_add_f32_e32 v183, 1.0, v183
	global_store_dwordx4 v[166:167], v[190:193], off nt
	v_rcp_f32_e32 v148, v148
	v_rcp_f32_e32 v163, v163
	v_rcp_f32_e32 v174, v174
	v_rcp_f32_e32 v175, v175
	v_rcp_f32_e32 v177, v177
	v_rcp_f32_e32 v181, v181
	v_rcp_f32_e32 v183, v183
	v_cvt_pk_bf16_f32 v190, v148, v163
	v_cvt_pk_bf16_f32 v191, v173, v174
	v_cvt_pk_bf16_f32 v192, v175, v177
	v_cvt_pk_bf16_f32 v193, v181, v183
	global_store_dwordx4 v[166:167], v[190:193], off offset:256 nt
	v_add_f32_e32 v166, v52, v140
	v_add_f32_e32 v167, v53, v141
	v_add_f32_e32 v173, v54, v142
	v_mul_f32_e32 v166, 0xbfb8aa3b, v166
	v_mul_f32_e32 v167, 0xbfb8aa3b, v167
	v_mul_f32_e32 v173, 0xbfb8aa3b, v173
	v_add_f32_e32 v174, v55, v143
	v_exp_f32_e32 v166, v166
	v_exp_f32_e32 v167, v167
	v_exp_f32_e32 v173, v173
	v_mul_f32_e32 v174, 0xbfb8aa3b, v174
	v_add_f32_e32 v175, v48, v136
	v_add_f32_e32 v177, v49, v137
	v_add_f32_e32 v181, v50, v138
	v_add_f32_e32 v183, v51, v139
	v_exp_f32_e32 v174, v174
	v_mul_f32_e32 v175, 0xbfb8aa3b, v175
	v_mul_f32_e32 v177, 0xbfb8aa3b, v177
	v_mul_f32_e32 v181, 0xbfb8aa3b, v181
	v_mul_f32_e32 v183, 0xbfb8aa3b, v183
	v_exp_f32_e32 v175, v175
	v_exp_f32_e32 v177, v177
	v_exp_f32_e32 v181, v181
	v_exp_f32_e32 v183, v183
	v_add_u32_e32 v148, 0x90, v162
	v_add_f32_e32 v166, 1.0, v166
	v_add_f32_e32 v167, 1.0, v167
	v_add_f32_e32 v173, 1.0, v173
	v_ashrrev_i32_e32 v163, 31, v148
	v_rcp_f32_e32 v166, v166
	v_rcp_f32_e32 v167, v167
	v_rcp_f32_e32 v173, v173
	v_add_f32_e32 v174, 1.0, v174
	v_rcp_f32_e32 v174, v174
	v_add_f32_e32 v175, 1.0, v175
	v_add_f32_e32 v177, 1.0, v177
	v_add_f32_e32 v181, 1.0, v181
	v_add_f32_e32 v183, 1.0, v183
	v_cvt_pk_bf16_f32 v190, v166, v167
	v_cvt_pk_bf16_f32 v191, v173, v174
	v_mul_lo_u32 v163, s28, v163
	v_mul_lo_u32 v173, s29, v148
	v_mad_u64_u32 v[166:167], s[10:11], s28, v148, 0
	v_rcp_f32_e32 v175, v175
	v_rcp_f32_e32 v177, v177
	v_rcp_f32_e32 v181, v181
	v_rcp_f32_e32 v183, v183
	v_add3_u32 v167, v167, v163, v173
	v_add_f32_e32 v173, v42, v134
	v_cvt_pk_bf16_f32 v192, v175, v177
	v_cvt_pk_bf16_f32 v193, v181, v183
	v_add_f32_e32 v148, v40, v132
	v_add_f32_e32 v163, v41, v133
	v_mul_f32_e32 v173, 0xbfb8aa3b, v173
	v_add_f32_e32 v174, v43, v135
	v_add_f32_e32 v175, v32, v128
	v_add_f32_e32 v177, v33, v129
	v_add_f32_e32 v181, v34, v130
	v_add_f32_e32 v183, v35, v131
	v_mul_f32_e32 v148, 0xbfb8aa3b, v148
	v_mul_f32_e32 v163, 0xbfb8aa3b, v163
	v_exp_f32_e32 v173, v173
	v_mul_f32_e32 v174, 0xbfb8aa3b, v174
	v_mul_f32_e32 v175, 0xbfb8aa3b, v175
	v_mul_f32_e32 v177, 0xbfb8aa3b, v177
	v_mul_f32_e32 v181, 0xbfb8aa3b, v181
	v_mul_f32_e32 v183, 0xbfb8aa3b, v183
	v_exp_f32_e32 v148, v148
	v_exp_f32_e32 v163, v163
	v_exp_f32_e32 v174, v174
	v_exp_f32_e32 v175, v175
	v_exp_f32_e32 v177, v177
	v_exp_f32_e32 v181, v181
	v_exp_f32_e32 v183, v183
	v_lshl_add_u64 v[166:167], v[166:167], 1, s[70:71]
	v_add_f32_e32 v173, 1.0, v173
	v_lshl_add_u64 v[166:167], v[166:167], 0, v[164:165]
	v_add_f32_e32 v148, 1.0, v148
	v_add_f32_e32 v163, 1.0, v163
	v_rcp_f32_e32 v173, v173
	v_add_f32_e32 v174, 1.0, v174
	v_add_f32_e32 v175, 1.0, v175
	v_add_f32_e32 v177, 1.0, v177
	v_add_f32_e32 v181, 1.0, v181
	v_add_f32_e32 v183, 1.0, v183
	global_store_dwordx4 v[166:167], v[190:193], off nt
	v_rcp_f32_e32 v148, v148
	v_rcp_f32_e32 v163, v163
	v_rcp_f32_e32 v174, v174
	v_rcp_f32_e32 v175, v175
	v_rcp_f32_e32 v177, v177
	v_rcp_f32_e32 v181, v181
	v_rcp_f32_e32 v183, v183
	v_cvt_pk_bf16_f32 v190, v148, v163
	v_cvt_pk_bf16_f32 v191, v173, v174
	v_cvt_pk_bf16_f32 v192, v175, v177
	v_cvt_pk_bf16_f32 v193, v181, v183
	global_store_dwordx4 v[166:167], v[190:193], off offset:256 nt
	v_add_f32_e32 v166, v28, v140
	v_add_f32_e32 v167, v29, v141
	v_add_f32_e32 v173, v30, v142
	v_mul_f32_e32 v166, 0xbfb8aa3b, v166
	v_mul_f32_e32 v167, 0xbfb8aa3b, v167
	v_mul_f32_e32 v173, 0xbfb8aa3b, v173
	v_add_f32_e32 v174, v31, v143
	v_add_f32_e32 v175, v20, v136
	v_add_f32_e32 v177, v21, v137
	v_add_f32_e32 v181, v22, v138
	v_add_f32_e32 v183, v23, v139
	v_exp_f32_e32 v166, v166
	v_exp_f32_e32 v167, v167
	v_exp_f32_e32 v173, v173
	v_mul_f32_e32 v174, 0xbfb8aa3b, v174
	v_mul_f32_e32 v175, 0xbfb8aa3b, v175
	v_mul_f32_e32 v177, 0xbfb8aa3b, v177
	v_mul_f32_e32 v181, 0xbfb8aa3b, v181
	v_mul_f32_e32 v183, 0xbfb8aa3b, v183
	v_exp_f32_e32 v174, v174
	v_exp_f32_e32 v175, v175
	v_exp_f32_e32 v177, v177
	v_exp_f32_e32 v181, v181
	v_exp_f32_e32 v183, v183
	v_add_u32_e32 v148, 0xa0, v162
	v_add_f32_e32 v166, 1.0, v166
	v_add_f32_e32 v167, 1.0, v167
	v_add_f32_e32 v173, 1.0, v173
	v_ashrrev_i32_e32 v163, 31, v148
	v_rcp_f32_e32 v166, v166
	v_rcp_f32_e32 v167, v167
	v_rcp_f32_e32 v173, v173
	v_add_f32_e32 v174, 1.0, v174
	v_add_f32_e32 v175, 1.0, v175
	v_add_f32_e32 v177, 1.0, v177
	v_add_f32_e32 v181, 1.0, v181
	v_add_f32_e32 v183, 1.0, v183
	v_rcp_f32_e32 v174, v174
	v_rcp_f32_e32 v175, v175
	v_rcp_f32_e32 v177, v177
	v_rcp_f32_e32 v181, v181
	v_rcp_f32_e32 v183, v183
	v_cvt_pk_bf16_f32 v190, v166, v167
	v_cvt_pk_bf16_f32 v191, v173, v174
	v_mul_lo_u32 v163, s28, v163
	v_mul_lo_u32 v173, s29, v148
	v_mad_u64_u32 v[166:167], s[10:11], s28, v148, 0
	v_cvt_pk_bf16_f32 v192, v175, v177
	v_cvt_pk_bf16_f32 v193, v181, v183
	v_add3_u32 v167, v167, v163, v173
	v_add_f32_e32 v148, v12, v132
	v_add_f32_e32 v163, v13, v133
	v_add_f32_e32 v173, v14, v134
	v_add_f32_e32 v174, v15, v135
	v_add_f32_e32 v175, v4, v128
	v_add_f32_e32 v177, v5, v129
	v_add_f32_e32 v181, v6, v130
	v_add_f32_e32 v183, v7, v131
	v_add_f32_e32 v136, v16, v136
	v_mul_f32_e32 v148, 0xbfb8aa3b, v148
	v_mul_f32_e32 v163, 0xbfb8aa3b, v163
	v_mul_f32_e32 v173, 0xbfb8aa3b, v173
	v_mul_f32_e32 v174, 0xbfb8aa3b, v174
	v_mul_f32_e32 v175, 0xbfb8aa3b, v175
	v_mul_f32_e32 v177, 0xbfb8aa3b, v177
	v_mul_f32_e32 v181, 0xbfb8aa3b, v181
	v_mul_f32_e32 v183, 0xbfb8aa3b, v183
	v_mul_f32_e32 v136, 0xbfb8aa3b, v136
	v_exp_f32_e32 v148, v148
	v_exp_f32_e32 v163, v163
	v_exp_f32_e32 v173, v173
	v_exp_f32_e32 v174, v174
	v_exp_f32_e32 v175, v175
	v_exp_f32_e32 v177, v177
	v_exp_f32_e32 v181, v181
	v_exp_f32_e32 v183, v183
	v_exp_f32_e32 v136, v136
	v_lshl_add_u64 v[166:167], v[166:167], 1, s[70:71]
	v_lshl_add_u64 v[166:167], v[166:167], 0, v[164:165]
	v_add_f32_e32 v148, 1.0, v148
	v_add_f32_e32 v163, 1.0, v163
	v_add_f32_e32 v173, 1.0, v173
	v_add_f32_e32 v174, 1.0, v174
	v_add_f32_e32 v175, 1.0, v175
	v_add_f32_e32 v177, 1.0, v177
	v_add_f32_e32 v181, 1.0, v181
	v_add_f32_e32 v183, 1.0, v183
	v_add_f32_e32 v136, 1.0, v136
	global_store_dwordx4 v[166:167], v[190:193], off nt
	v_rcp_f32_e32 v148, v148
	v_rcp_f32_e32 v163, v163
	v_rcp_f32_e32 v173, v173
	v_rcp_f32_e32 v174, v174
	v_rcp_f32_e32 v175, v175
	v_rcp_f32_e32 v177, v177
	v_rcp_f32_e32 v181, v181
	v_rcp_f32_e32 v183, v183
	v_cvt_pk_bf16_f32 v190, v148, v163
	v_cvt_pk_bf16_f32 v191, v173, v174
	v_cvt_pk_bf16_f32 v192, v175, v177
	v_cvt_pk_bf16_f32 v193, v181, v183
	global_store_dwordx4 v[166:167], v[190:193], off offset:256 nt
	v_rcp_f32_e32 v166, v136
	v_add_f32_e32 v136, v17, v137
	v_mul_f32_e32 v136, 0xbfb8aa3b, v136
	v_exp_f32_e32 v136, v136
	v_add_f32_e32 v140, v24, v140
	v_add_f32_e32 v141, v25, v141
	v_add_f32_e32 v142, v26, v142
	v_add_f32_e32 v136, 1.0, v136
	v_rcp_f32_e32 v167, v136
	v_add_f32_e32 v136, v18, v138
	v_mul_f32_e32 v136, 0xbfb8aa3b, v136
	v_exp_f32_e32 v136, v136
	v_add_f32_e32 v143, v27, v143
	v_mul_f32_e32 v140, 0xbfb8aa3b, v140
	v_mul_f32_e32 v141, 0xbfb8aa3b, v141
	v_add_f32_e32 v136, 1.0, v136
	v_mul_f32_e32 v142, 0xbfb8aa3b, v142
	v_mul_f32_e32 v143, 0xbfb8aa3b, v143
	v_rcp_f32_e32 v173, v136
	v_add_f32_e32 v136, v19, v139
	v_exp_f32_e32 v140, v140
	v_exp_f32_e32 v141, v141
	v_exp_f32_e32 v142, v142
	v_exp_f32_e32 v143, v143
	v_mul_f32_e32 v136, 0xbfb8aa3b, v136
	v_exp_f32_e32 v136, v136
	v_add_f32_e32 v128, v0, v128
	v_add_u32_e32 v148, 0xb0, v162
	v_add_f32_e32 v140, 1.0, v140
	v_add_f32_e32 v141, 1.0, v141
	v_add_f32_e32 v142, 1.0, v142
	v_add_f32_e32 v143, 1.0, v143
	v_mul_f32_e32 v128, 0xbfb8aa3b, v128
	v_ashrrev_i32_e32 v163, 31, v148
	v_rcp_f32_e32 v140, v140
	v_rcp_f32_e32 v141, v141
	v_rcp_f32_e32 v142, v142
	v_rcp_f32_e32 v143, v143
	v_add_f32_e32 v136, 1.0, v136
	v_exp_f32_e32 v128, v128
	v_rcp_f32_e32 v139, v136
	v_cvt_pk_bf16_f32 v136, v140, v141
	v_cvt_pk_bf16_f32 v137, v142, v143
	v_mul_lo_u32 v142, s28, v163
	v_mul_lo_u32 v143, s29, v148
	v_mad_u64_u32 v[140:141], s[10:11], s28, v148, 0
	v_add3_u32 v141, v141, v142, v143
	v_lshl_add_u64 v[140:141], v[140:141], 1, s[70:71]
	v_lshl_add_u64 v[140:141], v[140:141], 0, v[164:165]
	v_add_f32_e32 v128, 1.0, v128
	v_cvt_pk_bf16_f32 v138, v166, v167
	v_cvt_pk_bf16_f32 v139, v173, v139
	global_store_dwordx4 v[140:141], v[136:139], off nt
	v_add_f32_e32 v132, v8, v132
	v_add_f32_e32 v133, v9, v133
	v_rcp_f32_e32 v136, v128
	v_add_f32_e32 v128, v1, v129
	v_mul_f32_e32 v128, 0xbfb8aa3b, v128
	v_exp_f32_e32 v128, v128
	v_add_f32_e32 v134, v10, v134
	v_add_f32_e32 v135, v11, v135
	v_mul_f32_e32 v132, 0xbfb8aa3b, v132
	v_add_f32_e32 v128, 1.0, v128
	v_rcp_f32_e32 v137, v128
	v_add_f32_e32 v128, v2, v130
	v_mul_f32_e32 v128, 0xbfb8aa3b, v128
	v_exp_f32_e32 v128, v128
	v_mul_f32_e32 v133, 0xbfb8aa3b, v133
	v_mul_f32_e32 v134, 0xbfb8aa3b, v134
	v_mul_f32_e32 v135, 0xbfb8aa3b, v135
	v_add_f32_e32 v128, 1.0, v128
	v_rcp_f32_e32 v138, v128
	v_add_f32_e32 v128, v3, v131
	v_mul_f32_e32 v128, 0xbfb8aa3b, v128
	v_exp_f32_e32 v128, v128
	v_exp_f32_e32 v132, v132
	v_exp_f32_e32 v133, v133
	v_exp_f32_e32 v134, v134
	v_exp_f32_e32 v135, v135
	v_add_f32_e32 v128, 1.0, v128
	v_add_f32_e32 v132, 1.0, v132
	v_add_f32_e32 v133, 1.0, v133
	v_add_f32_e32 v134, 1.0, v134
	v_add_f32_e32 v135, 1.0, v135
	v_rcp_f32_e32 v131, v128
	v_rcp_f32_e32 v132, v132
	v_rcp_f32_e32 v133, v133
	v_rcp_f32_e32 v134, v134
	v_rcp_f32_e32 v135, v135
	v_cvt_pk_bf16_f32 v128, v132, v133
	v_cvt_pk_bf16_f32 v129, v134, v135
	v_cvt_pk_bf16_f32 v130, v136, v137
	v_cvt_pk_bf16_f32 v131, v138, v131
	global_store_dwordx4 v[140:141], v[128:131], off offset:256 nt

.LBB0_531:
	s_andn2_b64 vcc, exec, s[10:11]
	s_cbranch_vccnz .LBB0_533
	v_lshl_or_b32 v164, s25, 8, v186
	v_ashrrev_i32_e32 v165, 31, v164
	v_lshl_add_u64 v[166:167], v[164:165], 2, s[50:51]
	global_load_dwordx4 v[136:139], v[166:167], off offset:16
	global_load_dwordx4 v[140:143], v[166:167], off
	global_load_dwordx4 v[128:131], v[166:167], off offset:528
	global_load_dwordx4 v[132:135], v[166:167], off offset:512
	v_ashrrev_i32_e32 v148, 31, v162
	v_mul_lo_u32 v148, s28, v148
	v_lshlrev_b64 v[164:165], 1, v[164:165]
	s_waitcnt vmcnt(0)
	v_add_f32_e32 v174, v116, v136
	v_add_f32_e32 v163, v124, v140
	v_add_f32_e32 v166, v125, v141
	v_add_f32_e32 v167, v126, v142
	v_add_f32_e32 v173, v127, v143
	v_mul_f32_e32 v163, 0xbfb8aa3b, v163
	v_mul_f32_e32 v166, 0xbfb8aa3b, v166
	v_mul_f32_e32 v167, 0xbfb8aa3b, v167
	v_mul_f32_e32 v173, 0xbfb8aa3b, v173
	v_add_f32_e32 v175, v117, v137
	v_add_f32_e32 v177, v118, v138
	v_add_f32_e32 v181, v119, v139
	v_exp_f32_e32 v163, v163
	v_exp_f32_e32 v166, v166
	v_exp_f32_e32 v167, v167
	v_exp_f32_e32 v173, v173
	v_mul_f32_e32 v174, 0xbfb8aa3b, v174
	v_mul_f32_e32 v175, 0xbfb8aa3b, v175
	v_mul_f32_e32 v177, 0xbfb8aa3b, v177
	v_mul_f32_e32 v181, 0xbfb8aa3b, v181
	v_exp_f32_e32 v174, v174
	v_exp_f32_e32 v175, v175
	v_exp_f32_e32 v177, v177
	v_exp_f32_e32 v181, v181
	v_add_f32_e32 v163, 1.0, v163
	v_add_f32_e32 v166, 1.0, v166
	v_add_f32_e32 v167, 1.0, v167
	v_add_f32_e32 v173, 1.0, v173
	v_rcp_f32_e32 v163, v163
	v_rcp_f32_e32 v166, v166
	v_rcp_f32_e32 v167, v167
	v_rcp_f32_e32 v173, v173
	v_add_f32_e32 v174, 1.0, v174
	v_add_f32_e32 v175, 1.0, v175
	v_add_f32_e32 v177, 1.0, v177
	v_add_f32_e32 v181, 1.0, v181
	v_rcp_f32_e32 v174, v174
	v_rcp_f32_e32 v175, v175
	v_rcp_f32_e32 v177, v177
	v_rcp_f32_e32 v181, v181
	v_mul_f32_e32 v163, 0xbf1b4598, v163
	v_mul_f32_e32 v166, 0xbf1b4598, v166
	v_mul_f32_e32 v167, 0xbf1b4598, v167
	v_mul_f32_e32 v173, 0xbf1b4598, v173
	v_mul_f32_e32 v174, 0xbf1b4598, v174
	v_mul_f32_e32 v175, 0xbf1b4598, v175
	v_mul_f32_e32 v177, 0xbf1b4598, v177
	v_mul_f32_e32 v181, 0xbf1b4598, v181
	v_cvt_pk_bf16_f32 v190, v163, v166
	v_cvt_pk_bf16_f32 v191, v167, v173
	v_mul_lo_u32 v163, s29, v162
	v_mad_u64_u32 v[166:167], s[10:11], s28, v162, 0
	v_add_f32_e32 v173, v109, v133
	v_cvt_pk_bf16_f32 v192, v174, v175
	v_cvt_pk_bf16_f32 v193, v177, v181
	v_add3_u32 v167, v167, v148, v163
	v_add_f32_e32 v163, v108, v132
	v_mul_f32_e32 v173, 0xbfb8aa3b, v173
	v_add_f32_e32 v174, v110, v134
	v_add_f32_e32 v175, v111, v135
	v_add_f32_e32 v177, v100, v128
	v_add_f32_e32 v181, v101, v129
	v_add_f32_e32 v183, v102, v130
	v_add_f32_e32 v184, v103, v131
	v_mul_f32_e32 v163, 0xbfb8aa3b, v163
	v_exp_f32_e32 v173, v173
	v_mul_f32_e32 v174, 0xbfb8aa3b, v174
	v_mul_f32_e32 v175, 0xbfb8aa3b, v175
	v_mul_f32_e32 v177, 0xbfb8aa3b, v177
	v_mul_f32_e32 v181, 0xbfb8aa3b, v181
	v_mul_f32_e32 v183, 0xbfb8aa3b, v183
	v_mul_f32_e32 v184, 0xbfb8aa3b, v184
	v_exp_f32_e32 v163, v163
	v_exp_f32_e32 v174, v174
	v_exp_f32_e32 v175, v175
	v_exp_f32_e32 v177, v177
	v_exp_f32_e32 v181, v181
	v_exp_f32_e32 v183, v183
	v_exp_f32_e32 v184, v184
	v_add_f32_e32 v173, 1.0, v173
	v_add_f32_e32 v163, 1.0, v163
	v_rcp_f32_e32 v173, v173
	v_add_f32_e32 v174, 1.0, v174
	v_add_f32_e32 v175, 1.0, v175
	v_add_f32_e32 v177, 1.0, v177
	v_add_f32_e32 v181, 1.0, v181
	v_add_f32_e32 v183, 1.0, v183
	v_add_f32_e32 v184, 1.0, v184
	v_rcp_f32_e32 v163, v163
	v_rcp_f32_e32 v174, v174
	v_rcp_f32_e32 v175, v175
	v_rcp_f32_e32 v177, v177
	v_rcp_f32_e32 v181, v181
	v_rcp_f32_e32 v183, v183
	v_rcp_f32_e32 v184, v184
	v_lshl_add_u64 v[166:167], v[166:167], 1, s[70:71]
	v_lshl_add_u64 v[166:167], v[166:167], 0, v[164:165]
	v_mul_f32_e32 v173, 0xbf1b4598, v173
	global_store_dwordx4 v[166:167], v[190:193], off nt
	v_mul_f32_e32 v163, 0xbf1b4598, v163
	v_mul_f32_e32 v174, 0xbf1b4598, v174
	v_mul_f32_e32 v175, 0xbf1b4598, v175
	v_mul_f32_e32 v177, 0xbf1b4598, v177
	v_mul_f32_e32 v181, 0xbf1b4598, v181
	v_mul_f32_e32 v183, 0xbf1b4598, v183
	v_mul_f32_e32 v184, 0xbf1b4598, v184
	v_cvt_pk_bf16_f32 v190, v163, v173
	v_cvt_pk_bf16_f32 v191, v174, v175
	v_cvt_pk_bf16_f32 v192, v177, v181
	v_cvt_pk_bf16_f32 v193, v183, v184
	global_store_dwordx4 v[166:167], v[190:193], off offset:256 nt
	v_add_f32_e32 v166, v120, v140
	v_add_f32_e32 v167, v121, v141
	v_add_f32_e32 v173, v122, v142
	v_mul_f32_e32 v166, 0xbfb8aa3b, v166
	v_mul_f32_e32 v167, 0xbfb8aa3b, v167
	v_mul_f32_e32 v173, 0xbfb8aa3b, v173
	v_add_f32_e32 v174, v123, v143
	v_exp_f32_e32 v166, v166
	v_exp_f32_e32 v167, v167
	v_exp_f32_e32 v173, v173
	v_mul_f32_e32 v174, 0xbfb8aa3b, v174
	v_add_f32_e32 v175, v112, v136
	v_add_f32_e32 v177, v113, v137
	v_add_f32_e32 v181, v114, v138
	v_add_f32_e32 v183, v115, v139
	v_exp_f32_e32 v174, v174
	v_mul_f32_e32 v175, 0xbfb8aa3b, v175
	v_mul_f32_e32 v177, 0xbfb8aa3b, v177
	v_mul_f32_e32 v181, 0xbfb8aa3b, v181
	v_mul_f32_e32 v183, 0xbfb8aa3b, v183
	v_exp_f32_e32 v175, v175
	v_exp_f32_e32 v177, v177
	v_exp_f32_e32 v181, v181
	v_exp_f32_e32 v183, v183
	v_add_f32_e32 v166, 1.0, v166
	v_add_f32_e32 v167, 1.0, v167
	v_add_f32_e32 v173, 1.0, v173
	v_rcp_f32_e32 v166, v166
	v_rcp_f32_e32 v167, v167
	v_rcp_f32_e32 v173, v173
	v_add_f32_e32 v174, 1.0, v174
	v_rcp_f32_e32 v174, v174
	v_add_f32_e32 v175, 1.0, v175
	v_add_f32_e32 v177, 1.0, v177
	v_add_f32_e32 v181, 1.0, v181
	v_add_f32_e32 v183, 1.0, v183
	v_rcp_f32_e32 v175, v175
	v_rcp_f32_e32 v177, v177
	v_rcp_f32_e32 v181, v181
	v_rcp_f32_e32 v183, v183
	v_or_b32_e32 v163, 16, v162
	v_mul_f32_e32 v166, 0xbf1b4598, v166
	v_mul_f32_e32 v167, 0xbf1b4598, v167
	v_mul_f32_e32 v173, 0xbf1b4598, v173
	v_mul_f32_e32 v174, 0xbf1b4598, v174
	v_cvt_pk_bf16_f32 v190, v166, v167
	v_cvt_pk_bf16_f32 v191, v173, v174
	v_mul_lo_u32 v173, s29, v163
	v_mad_u64_u32 v[166:167], s[10:11], s28, v163, 0
	v_mul_f32_e32 v175, 0xbf1b4598, v175
	v_mul_f32_e32 v177, 0xbf1b4598, v177
	v_mul_f32_e32 v181, 0xbf1b4598, v181
	v_mul_f32_e32 v183, 0xbf1b4598, v183
	v_add3_u32 v167, v167, v148, v173
	v_add_f32_e32 v173, v105, v133
	v_cvt_pk_bf16_f32 v192, v175, v177
	v_cvt_pk_bf16_f32 v193, v181, v183
	v_add_f32_e32 v163, v104, v132
	v_mul_f32_e32 v173, 0xbfb8aa3b, v173
	v_add_f32_e32 v174, v106, v134
	v_add_f32_e32 v175, v107, v135
	v_add_f32_e32 v177, v96, v128
	v_add_f32_e32 v181, v97, v129
	v_add_f32_e32 v183, v98, v130
	v_add_f32_e32 v184, v99, v131
	v_mul_f32_e32 v163, 0xbfb8aa3b, v163
	v_exp_f32_e32 v173, v173
	v_mul_f32_e32 v174, 0xbfb8aa3b, v174
	v_mul_f32_e32 v175, 0xbfb8aa3b, v175
	v_mul_f32_e32 v177, 0xbfb8aa3b, v177
	v_mul_f32_e32 v181, 0xbfb8aa3b, v181
	v_mul_f32_e32 v183, 0xbfb8aa3b, v183
	v_mul_f32_e32 v184, 0xbfb8aa3b, v184
	v_exp_f32_e32 v163, v163
	v_exp_f32_e32 v174, v174
	v_exp_f32_e32 v175, v175
	v_exp_f32_e32 v177, v177
	v_exp_f32_e32 v181, v181
	v_exp_f32_e32 v183, v183
	v_exp_f32_e32 v184, v184
	v_add_f32_e32 v173, 1.0, v173
	v_add_f32_e32 v163, 1.0, v163
	v_rcp_f32_e32 v173, v173
	v_add_f32_e32 v174, 1.0, v174
	v_add_f32_e32 v175, 1.0, v175
	v_add_f32_e32 v177, 1.0, v177
	v_add_f32_e32 v181, 1.0, v181
	v_add_f32_e32 v183, 1.0, v183
	v_add_f32_e32 v184, 1.0, v184
	v_rcp_f32_e32 v163, v163
	v_rcp_f32_e32 v174, v174
	v_rcp_f32_e32 v175, v175
	v_rcp_f32_e32 v177, v177
	v_rcp_f32_e32 v181, v181
	v_rcp_f32_e32 v183, v183
	v_rcp_f32_e32 v184, v184
	v_lshl_add_u64 v[166:167], v[166:167], 1, s[70:71]
	v_lshl_add_u64 v[166:167], v[166:167], 0, v[164:165]
	v_mul_f32_e32 v173, 0xbf1b4598, v173
	global_store_dwordx4 v[166:167], v[190:193], off nt
	v_mul_f32_e32 v163, 0xbf1b4598, v163
	v_mul_f32_e32 v174, 0xbf1b4598, v174
	v_mul_f32_e32 v175, 0xbf1b4598, v175
	v_mul_f32_e32 v177, 0xbf1b4598, v177
	v_mul_f32_e32 v181, 0xbf1b4598, v181
	v_mul_f32_e32 v183, 0xbf1b4598, v183
	v_mul_f32_e32 v184, 0xbf1b4598, v184
	v_cvt_pk_bf16_f32 v190, v163, v173
	v_cvt_pk_bf16_f32 v191, v174, v175
	v_cvt_pk_bf16_f32 v192, v177, v181
	v_cvt_pk_bf16_f32 v193, v183, v184
	global_store_dwordx4 v[166:167], v[190:193], off offset:256 nt
	v_add_f32_e32 v166, v92, v140
	v_add_f32_e32 v167, v93, v141
	v_add_f32_e32 v173, v94, v142
	v_mul_f32_e32 v166, 0xbfb8aa3b, v166
	v_mul_f32_e32 v167, 0xbfb8aa3b, v167
	v_mul_f32_e32 v173, 0xbfb8aa3b, v173
	v_add_f32_e32 v174, v95, v143
	v_exp_f32_e32 v166, v166
	v_exp_f32_e32 v167, v167
	v_exp_f32_e32 v173, v173
	v_mul_f32_e32 v174, 0xbfb8aa3b, v174
	v_add_f32_e32 v175, v84, v136
	v_add_f32_e32 v177, v85, v137
	v_add_f32_e32 v181, v86, v138
	v_add_f32_e32 v183, v87, v139
	v_exp_f32_e32 v174, v174
	v_mul_f32_e32 v175, 0xbfb8aa3b, v175
	v_mul_f32_e32 v177, 0xbfb8aa3b, v177
	v_mul_f32_e32 v181, 0xbfb8aa3b, v181
	v_mul_f32_e32 v183, 0xbfb8aa3b, v183
	v_exp_f32_e32 v175, v175
	v_exp_f32_e32 v177, v177
	v_exp_f32_e32 v181, v181
	v_exp_f32_e32 v183, v183
	v_add_f32_e32 v166, 1.0, v166
	v_add_f32_e32 v167, 1.0, v167
	v_add_f32_e32 v173, 1.0, v173
	v_rcp_f32_e32 v166, v166
	v_rcp_f32_e32 v167, v167
	v_rcp_f32_e32 v173, v173
	v_add_f32_e32 v174, 1.0, v174
	v_rcp_f32_e32 v174, v174
	v_add_f32_e32 v175, 1.0, v175
	v_add_f32_e32 v177, 1.0, v177
	v_add_f32_e32 v181, 1.0, v181
	v_add_f32_e32 v183, 1.0, v183
	v_rcp_f32_e32 v175, v175
	v_rcp_f32_e32 v177, v177
	v_rcp_f32_e32 v181, v181
	v_rcp_f32_e32 v183, v183
	v_or_b32_e32 v163, 32, v162
	v_mul_f32_e32 v166, 0xbf1b4598, v166
	v_mul_f32_e32 v167, 0xbf1b4598, v167
	v_mul_f32_e32 v173, 0xbf1b4598, v173
	v_mul_f32_e32 v174, 0xbf1b4598, v174
	v_cvt_pk_bf16_f32 v190, v166, v167
	v_cvt_pk_bf16_f32 v191, v173, v174
	v_mul_lo_u32 v173, s29, v163
	v_mad_u64_u32 v[166:167], s[10:11], s28, v163, 0
	v_mul_f32_e32 v175, 0xbf1b4598, v175
	v_mul_f32_e32 v177, 0xbf1b4598, v177
	v_mul_f32_e32 v181, 0xbf1b4598, v181
	v_mul_f32_e32 v183, 0xbf1b4598, v183
	v_add3_u32 v167, v167, v148, v173
	v_add_f32_e32 v173, v77, v133
	v_cvt_pk_bf16_f32 v192, v175, v177
	v_cvt_pk_bf16_f32 v193, v181, v183
	v_add_f32_e32 v163, v76, v132
	v_mul_f32_e32 v173, 0xbfb8aa3b, v173
	v_add_f32_e32 v174, v78, v134
	v_add_f32_e32 v175, v79, v135
	v_add_f32_e32 v177, v68, v128
	v_add_f32_e32 v181, v69, v129
	v_add_f32_e32 v183, v70, v130
	v_add_f32_e32 v184, v71, v131
	v_mul_f32_e32 v163, 0xbfb8aa3b, v163
	v_exp_f32_e32 v173, v173
	v_mul_f32_e32 v174, 0xbfb8aa3b, v174
	v_mul_f32_e32 v175, 0xbfb8aa3b, v175
	v_mul_f32_e32 v177, 0xbfb8aa3b, v177
	v_mul_f32_e32 v181, 0xbfb8aa3b, v181
	v_mul_f32_e32 v183, 0xbfb8aa3b, v183
	v_mul_f32_e32 v184, 0xbfb8aa3b, v184
	v_exp_f32_e32 v163, v163
	v_exp_f32_e32 v174, v174
	v_exp_f32_e32 v175, v175
	v_exp_f32_e32 v177, v177
	v_exp_f32_e32 v181, v181
	v_exp_f32_e32 v183, v183
	v_exp_f32_e32 v184, v184
	v_add_f32_e32 v173, 1.0, v173
	v_add_f32_e32 v163, 1.0, v163
	v_rcp_f32_e32 v173, v173
	v_add_f32_e32 v174, 1.0, v174
	v_add_f32_e32 v175, 1.0, v175
	v_add_f32_e32 v177, 1.0, v177
	v_add_f32_e32 v181, 1.0, v181
	v_add_f32_e32 v183, 1.0, v183
	v_add_f32_e32 v184, 1.0, v184
	v_rcp_f32_e32 v163, v163
	v_rcp_f32_e32 v174, v174
	v_rcp_f32_e32 v175, v175
	v_rcp_f32_e32 v177, v177
	v_rcp_f32_e32 v181, v181
	v_rcp_f32_e32 v183, v183
	v_rcp_f32_e32 v184, v184
	v_lshl_add_u64 v[166:167], v[166:167], 1, s[70:71]
	v_lshl_add_u64 v[166:167], v[166:167], 0, v[164:165]
	v_mul_f32_e32 v173, 0xbf1b4598, v173
	global_store_dwordx4 v[166:167], v[190:193], off nt
	v_mul_f32_e32 v163, 0xbf1b4598, v163
	v_mul_f32_e32 v174, 0xbf1b4598, v174
	v_mul_f32_e32 v175, 0xbf1b4598, v175
	v_mul_f32_e32 v177, 0xbf1b4598, v177
	v_mul_f32_e32 v181, 0xbf1b4598, v181
	v_mul_f32_e32 v183, 0xbf1b4598, v183
	v_mul_f32_e32 v184, 0xbf1b4598, v184
	v_cvt_pk_bf16_f32 v190, v163, v173
	v_cvt_pk_bf16_f32 v191, v174, v175
	v_cvt_pk_bf16_f32 v192, v177, v181
	v_cvt_pk_bf16_f32 v193, v183, v184
	global_store_dwordx4 v[166:167], v[190:193], off offset:256 nt
	v_add_f32_e32 v166, v88, v140
	v_add_f32_e32 v167, v89, v141
	v_add_f32_e32 v173, v90, v142
	v_mul_f32_e32 v166, 0xbfb8aa3b, v166
	v_mul_f32_e32 v167, 0xbfb8aa3b, v167
	v_mul_f32_e32 v173, 0xbfb8aa3b, v173
	v_add_f32_e32 v174, v91, v143
	v_exp_f32_e32 v166, v166
	v_exp_f32_e32 v167, v167
	v_exp_f32_e32 v173, v173
	v_mul_f32_e32 v174, 0xbfb8aa3b, v174
	v_add_f32_e32 v175, v80, v136
	v_add_f32_e32 v177, v81, v137
	v_add_f32_e32 v181, v82, v138
	v_add_f32_e32 v183, v83, v139
	v_exp_f32_e32 v174, v174
	v_mul_f32_e32 v175, 0xbfb8aa3b, v175
	v_mul_f32_e32 v177, 0xbfb8aa3b, v177
	v_mul_f32_e32 v181, 0xbfb8aa3b, v181
	v_mul_f32_e32 v183, 0xbfb8aa3b, v183
	v_exp_f32_e32 v175, v175
	v_exp_f32_e32 v177, v177
	v_exp_f32_e32 v181, v181
	v_exp_f32_e32 v183, v183
	v_add_f32_e32 v166, 1.0, v166
	v_add_f32_e32 v167, 1.0, v167
	v_add_f32_e32 v173, 1.0, v173
	v_rcp_f32_e32 v166, v166
	v_rcp_f32_e32 v167, v167
	v_rcp_f32_e32 v173, v173
	v_add_f32_e32 v174, 1.0, v174
	v_rcp_f32_e32 v174, v174
	v_add_f32_e32 v175, 1.0, v175
	v_add_f32_e32 v177, 1.0, v177
	v_add_f32_e32 v181, 1.0, v181
	v_add_f32_e32 v183, 1.0, v183
	v_rcp_f32_e32 v175, v175
	v_rcp_f32_e32 v177, v177
	v_rcp_f32_e32 v181, v181
	v_rcp_f32_e32 v183, v183
	v_or_b32_e32 v163, 48, v162
	v_mul_f32_e32 v166, 0xbf1b4598, v166
	v_mul_f32_e32 v167, 0xbf1b4598, v167
	v_mul_f32_e32 v173, 0xbf1b4598, v173
	v_mul_f32_e32 v174, 0xbf1b4598, v174
	v_cvt_pk_bf16_f32 v190, v166, v167
	v_cvt_pk_bf16_f32 v191, v173, v174
	v_mul_lo_u32 v173, s29, v163
	v_mad_u64_u32 v[166:167], s[10:11], s28, v163, 0
	v_mul_f32_e32 v175, 0xbf1b4598, v175
	v_mul_f32_e32 v177, 0xbf1b4598, v177
	v_mul_f32_e32 v181, 0xbf1b4598, v181
	v_mul_f32_e32 v183, 0xbf1b4598, v183
	v_add3_u32 v167, v167, v148, v173
	v_add_f32_e32 v173, v74, v134
	v_cvt_pk_bf16_f32 v192, v175, v177
	v_cvt_pk_bf16_f32 v193, v181, v183
	v_add_f32_e32 v148, v72, v132
	v_add_f32_e32 v163, v73, v133
	v_mul_f32_e32 v173, 0xbfb8aa3b, v173
	v_add_f32_e32 v174, v75, v135
	v_add_f32_e32 v175, v64, v128
	v_add_f32_e32 v177, v65, v129
	v_add_f32_e32 v181, v66, v130
	v_add_f32_e32 v183, v67, v131
	v_mul_f32_e32 v148, 0xbfb8aa3b, v148
	v_mul_f32_e32 v163, 0xbfb8aa3b, v163
	v_exp_f32_e32 v173, v173
	v_mul_f32_e32 v174, 0xbfb8aa3b, v174
	v_mul_f32_e32 v175, 0xbfb8aa3b, v175
	v_mul_f32_e32 v177, 0xbfb8aa3b, v177
	v_mul_f32_e32 v181, 0xbfb8aa3b, v181
	v_mul_f32_e32 v183, 0xbfb8aa3b, v183
	v_exp_f32_e32 v148, v148
	v_exp_f32_e32 v163, v163
	v_exp_f32_e32 v174, v174
	v_exp_f32_e32 v175, v175
	v_exp_f32_e32 v177, v177
	v_exp_f32_e32 v181, v181
	v_exp_f32_e32 v183, v183
	v_add_f32_e32 v173, 1.0, v173
	v_add_f32_e32 v148, 1.0, v148
	v_add_f32_e32 v163, 1.0, v163
	v_rcp_f32_e32 v173, v173
	v_add_f32_e32 v174, 1.0, v174
	v_add_f32_e32 v175, 1.0, v175
	v_add_f32_e32 v177, 1.0, v177
	v_add_f32_e32 v181, 1.0, v181
	v_add_f32_e32 v183, 1.0, v183
	v_rcp_f32_e32 v148, v148
	v_rcp_f32_e32 v163, v163
	v_rcp_f32_e32 v174, v174
	v_rcp_f32_e32 v175, v175
	v_rcp_f32_e32 v177, v177
	v_rcp_f32_e32 v181, v181
	v_rcp_f32_e32 v183, v183
	v_lshl_add_u64 v[166:167], v[166:167], 1, s[70:71]
	v_lshl_add_u64 v[166:167], v[166:167], 0, v[164:165]
	v_mul_f32_e32 v173, 0xbf1b4598, v173
	global_store_dwordx4 v[166:167], v[190:193], off nt
	v_mul_f32_e32 v148, 0xbf1b4598, v148
	v_mul_f32_e32 v163, 0xbf1b4598, v163
	v_mul_f32_e32 v174, 0xbf1b4598, v174
	v_mul_f32_e32 v175, 0xbf1b4598, v175
	v_mul_f32_e32 v177, 0xbf1b4598, v177
	v_mul_f32_e32 v181, 0xbf1b4598, v181
	v_mul_f32_e32 v183, 0xbf1b4598, v183
	v_cvt_pk_bf16_f32 v190, v148, v163
	v_cvt_pk_bf16_f32 v191, v173, v174
	v_cvt_pk_bf16_f32 v192, v175, v177
	v_cvt_pk_bf16_f32 v193, v181, v183
	global_store_dwordx4 v[166:167], v[190:193], off offset:256 nt
	v_add_f32_e32 v166, v60, v140
	v_add_f32_e32 v167, v61, v141
	v_add_f32_e32 v173, v62, v142
	v_mul_f32_e32 v166, 0xbfb8aa3b, v166
	v_mul_f32_e32 v167, 0xbfb8aa3b, v167
	v_mul_f32_e32 v173, 0xbfb8aa3b, v173
	v_add_f32_e32 v174, v63, v143
	v_exp_f32_e32 v166, v166
	v_exp_f32_e32 v167, v167
	v_exp_f32_e32 v173, v173
	v_mul_f32_e32 v174, 0xbfb8aa3b, v174
	v_add_f32_e32 v175, v56, v136
	v_add_f32_e32 v177, v57, v137
	v_add_f32_e32 v181, v58, v138
	v_add_f32_e32 v183, v59, v139
	v_exp_f32_e32 v174, v174
	v_mul_f32_e32 v175, 0xbfb8aa3b, v175
	v_mul_f32_e32 v177, 0xbfb8aa3b, v177
	v_mul_f32_e32 v181, 0xbfb8aa3b, v181
	v_mul_f32_e32 v183, 0xbfb8aa3b, v183
	v_exp_f32_e32 v175, v175
	v_exp_f32_e32 v177, v177
	v_exp_f32_e32 v181, v181
	v_exp_f32_e32 v183, v183
	v_add_f32_e32 v166, 1.0, v166
	v_add_f32_e32 v167, 1.0, v167
	v_add_f32_e32 v173, 1.0, v173
	v_rcp_f32_e32 v166, v166
	v_rcp_f32_e32 v167, v167
	v_rcp_f32_e32 v173, v173
	v_add_f32_e32 v174, 1.0, v174
	v_rcp_f32_e32 v174, v174
	v_add_f32_e32 v175, 1.0, v175
	v_add_f32_e32 v177, 1.0, v177
	v_add_f32_e32 v181, 1.0, v181
	v_add_f32_e32 v183, 1.0, v183
	v_rcp_f32_e32 v175, v175
	v_rcp_f32_e32 v177, v177
	v_rcp_f32_e32 v181, v181
	v_rcp_f32_e32 v183, v183
	v_add_u32_e32 v148, 0x80, v162
	v_ashrrev_i32_e32 v163, 31, v148
	v_mul_f32_e32 v166, 0xbf1b4598, v166
	v_mul_f32_e32 v167, 0xbf1b4598, v167
	v_mul_f32_e32 v173, 0xbf1b4598, v173
	v_mul_f32_e32 v174, 0xbf1b4598, v174
	v_cvt_pk_bf16_f32 v190, v166, v167
	v_cvt_pk_bf16_f32 v191, v173, v174
	v_mul_lo_u32 v163, s28, v163
	v_mul_lo_u32 v173, s29, v148
	v_mad_u64_u32 v[166:167], s[10:11], s28, v148, 0
	v_mul_f32_e32 v175, 0xbf1b4598, v175
	v_mul_f32_e32 v177, 0xbf1b4598, v177
	v_mul_f32_e32 v181, 0xbf1b4598, v181
	v_mul_f32_e32 v183, 0xbf1b4598, v183
	v_add3_u32 v167, v167, v163, v173
	v_add_f32_e32 v173, v46, v134
	v_cvt_pk_bf16_f32 v192, v175, v177
	v_cvt_pk_bf16_f32 v193, v181, v183
	v_add_f32_e32 v148, v44, v132
	v_add_f32_e32 v163, v45, v133
	v_mul_f32_e32 v173, 0xbfb8aa3b, v173
	v_add_f32_e32 v174, v47, v135
	v_add_f32_e32 v175, v36, v128
	v_add_f32_e32 v177, v37, v129
	v_add_f32_e32 v181, v38, v130
	v_add_f32_e32 v183, v39, v131
	v_mul_f32_e32 v148, 0xbfb8aa3b, v148
	v_mul_f32_e32 v163, 0xbfb8aa3b, v163
	v_exp_f32_e32 v173, v173
	v_mul_f32_e32 v174, 0xbfb8aa3b, v174
	v_mul_f32_e32 v175, 0xbfb8aa3b, v175
	v_mul_f32_e32 v177, 0xbfb8aa3b, v177
	v_mul_f32_e32 v181, 0xbfb8aa3b, v181
	v_mul_f32_e32 v183, 0xbfb8aa3b, v183
	v_exp_f32_e32 v148, v148
	v_exp_f32_e32 v163, v163
	v_exp_f32_e32 v174, v174
	v_exp_f32_e32 v175, v175
	v_exp_f32_e32 v177, v177
	v_exp_f32_e32 v181, v181
	v_exp_f32_e32 v183, v183
	v_add_f32_e32 v173, 1.0, v173
	v_add_f32_e32 v148, 1.0, v148
	v_add_f32_e32 v163, 1.0, v163
	v_rcp_f32_e32 v173, v173
	v_add_f32_e32 v174, 1.0, v174
	v_add_f32_e32 v175, 1.0, v175
	v_add_f32_e32 v177, 1.0, v177
	v_add_f32_e32 v181, 1.0, v181
	v_add_f32_e32 v183, 1.0, v183
	v_rcp_f32_e32 v148, v148
	v_rcp_f32_e32 v163, v163
	v_rcp_f32_e32 v174, v174
	v_rcp_f32_e32 v175, v175
	v_rcp_f32_e32 v177, v177
	v_rcp_f32_e32 v181, v181
	v_rcp_f32_e32 v183, v183
	v_lshl_add_u64 v[166:167], v[166:167], 1, s[70:71]
	v_lshl_add_u64 v[166:167], v[166:167], 0, v[164:165]
	v_mul_f32_e32 v173, 0xbf1b4598, v173
	global_store_dwordx4 v[166:167], v[190:193], off nt
	v_mul_f32_e32 v148, 0xbf1b4598, v148
	v_mul_f32_e32 v163, 0xbf1b4598, v163
	v_mul_f32_e32 v174, 0xbf1b4598, v174
	v_mul_f32_e32 v175, 0xbf1b4598, v175
	v_mul_f32_e32 v177, 0xbf1b4598, v177
	v_mul_f32_e32 v181, 0xbf1b4598, v181
	v_mul_f32_e32 v183, 0xbf1b4598, v183
	v_cvt_pk_bf16_f32 v190, v148, v163
	v_cvt_pk_bf16_f32 v191, v173, v174
	v_cvt_pk_bf16_f32 v192, v175, v177
	v_cvt_pk_bf16_f32 v193, v181, v183
	global_store_dwordx4 v[166:167], v[190:193], off offset:256 nt
	v_add_f32_e32 v166, v52, v140
	v_add_f32_e32 v167, v53, v141
	v_add_f32_e32 v173, v54, v142
	v_mul_f32_e32 v166, 0xbfb8aa3b, v166
	v_mul_f32_e32 v167, 0xbfb8aa3b, v167
	v_mul_f32_e32 v173, 0xbfb8aa3b, v173
	v_add_f32_e32 v174, v55, v143
	v_exp_f32_e32 v166, v166
	v_exp_f32_e32 v167, v167
	v_exp_f32_e32 v173, v173
	v_mul_f32_e32 v174, 0xbfb8aa3b, v174
	v_add_f32_e32 v175, v48, v136
	v_add_f32_e32 v177, v49, v137
	v_add_f32_e32 v181, v50, v138
	v_add_f32_e32 v183, v51, v139
	v_exp_f32_e32 v174, v174
	v_mul_f32_e32 v175, 0xbfb8aa3b, v175
	v_mul_f32_e32 v177, 0xbfb8aa3b, v177
	v_mul_f32_e32 v181, 0xbfb8aa3b, v181
	v_mul_f32_e32 v183, 0xbfb8aa3b, v183
	v_exp_f32_e32 v175, v175
	v_exp_f32_e32 v177, v177
	v_exp_f32_e32 v181, v181
	v_exp_f32_e32 v183, v183
	v_add_f32_e32 v166, 1.0, v166
	v_add_f32_e32 v167, 1.0, v167
	v_add_f32_e32 v173, 1.0, v173
	v_rcp_f32_e32 v166, v166
	v_rcp_f32_e32 v167, v167
	v_rcp_f32_e32 v173, v173
	v_add_f32_e32 v174, 1.0, v174
	v_rcp_f32_e32 v174, v174
	v_add_f32_e32 v175, 1.0, v175
	v_add_f32_e32 v177, 1.0, v177
	v_add_f32_e32 v181, 1.0, v181
	v_add_f32_e32 v183, 1.0, v183
	v_rcp_f32_e32 v175, v175
	v_rcp_f32_e32 v177, v177
	v_rcp_f32_e32 v181, v181
	v_rcp_f32_e32 v183, v183
	v_add_u32_e32 v148, 0x90, v162
	v_ashrrev_i32_e32 v163, 31, v148
	v_mul_f32_e32 v166, 0xbf1b4598, v166
	v_mul_f32_e32 v167, 0xbf1b4598, v167
	v_mul_f32_e32 v173, 0xbf1b4598, v173
	v_mul_f32_e32 v174, 0xbf1b4598, v174
	v_cvt_pk_bf16_f32 v190, v166, v167
	v_cvt_pk_bf16_f32 v191, v173, v174
	v_mul_lo_u32 v163, s28, v163
	v_mul_lo_u32 v173, s29, v148
	v_mad_u64_u32 v[166:167], s[10:11], s28, v148, 0
	v_mul_f32_e32 v175, 0xbf1b4598, v175
	v_mul_f32_e32 v177, 0xbf1b4598, v177
	v_mul_f32_e32 v181, 0xbf1b4598, v181
	v_mul_f32_e32 v183, 0xbf1b4598, v183
	v_add3_u32 v167, v167, v163, v173
	v_add_f32_e32 v173, v42, v134
	v_cvt_pk_bf16_f32 v192, v175, v177
	v_cvt_pk_bf16_f32 v193, v181, v183
	v_add_f32_e32 v148, v40, v132
	v_add_f32_e32 v163, v41, v133
	v_mul_f32_e32 v173, 0xbfb8aa3b, v173
	v_add_f32_e32 v174, v43, v135
	v_add_f32_e32 v175, v32, v128
	v_add_f32_e32 v177, v33, v129
	v_add_f32_e32 v181, v34, v130
	v_add_f32_e32 v183, v35, v131
	v_mul_f32_e32 v148, 0xbfb8aa3b, v148
	v_mul_f32_e32 v163, 0xbfb8aa3b, v163
	v_exp_f32_e32 v173, v173
	v_mul_f32_e32 v174, 0xbfb8aa3b, v174
	v_mul_f32_e32 v175, 0xbfb8aa3b, v175
	v_mul_f32_e32 v177, 0xbfb8aa3b, v177
	v_mul_f32_e32 v181, 0xbfb8aa3b, v181
	v_mul_f32_e32 v183, 0xbfb8aa3b, v183
	v_exp_f32_e32 v148, v148
	v_exp_f32_e32 v163, v163
	v_exp_f32_e32 v174, v174
	v_exp_f32_e32 v175, v175
	v_exp_f32_e32 v177, v177
	v_exp_f32_e32 v181, v181
	v_exp_f32_e32 v183, v183
	v_add_f32_e32 v173, 1.0, v173
	v_add_f32_e32 v148, 1.0, v148
	v_add_f32_e32 v163, 1.0, v163
	v_rcp_f32_e32 v173, v173
	v_add_f32_e32 v174, 1.0, v174
	v_add_f32_e32 v175, 1.0, v175
	v_add_f32_e32 v177, 1.0, v177
	v_add_f32_e32 v181, 1.0, v181
	v_add_f32_e32 v183, 1.0, v183
	v_rcp_f32_e32 v148, v148
	v_rcp_f32_e32 v163, v163
	v_rcp_f32_e32 v174, v174
	v_rcp_f32_e32 v175, v175
	v_rcp_f32_e32 v177, v177
	v_rcp_f32_e32 v181, v181
	v_rcp_f32_e32 v183, v183
	v_lshl_add_u64 v[166:167], v[166:167], 1, s[70:71]
	v_lshl_add_u64 v[166:167], v[166:167], 0, v[164:165]
	v_mul_f32_e32 v173, 0xbf1b4598, v173
	global_store_dwordx4 v[166:167], v[190:193], off nt
	v_mul_f32_e32 v148, 0xbf1b4598, v148
	v_mul_f32_e32 v163, 0xbf1b4598, v163
	v_mul_f32_e32 v174, 0xbf1b4598, v174
	v_mul_f32_e32 v175, 0xbf1b4598, v175
	v_mul_f32_e32 v177, 0xbf1b4598, v177
	v_mul_f32_e32 v181, 0xbf1b4598, v181
	v_mul_f32_e32 v183, 0xbf1b4598, v183
	v_cvt_pk_bf16_f32 v190, v148, v163
	v_cvt_pk_bf16_f32 v191, v173, v174
	v_cvt_pk_bf16_f32 v192, v175, v177
	v_cvt_pk_bf16_f32 v193, v181, v183
	global_store_dwordx4 v[166:167], v[190:193], off offset:256 nt
	v_add_f32_e32 v166, v28, v140
	v_add_f32_e32 v167, v29, v141
	v_add_f32_e32 v173, v30, v142
	v_mul_f32_e32 v166, 0xbfb8aa3b, v166
	v_mul_f32_e32 v167, 0xbfb8aa3b, v167
	v_mul_f32_e32 v173, 0xbfb8aa3b, v173
	v_add_f32_e32 v174, v31, v143
	v_add_f32_e32 v175, v20, v136
	v_add_f32_e32 v177, v21, v137
	v_add_f32_e32 v181, v22, v138
	v_add_f32_e32 v183, v23, v139
	v_exp_f32_e32 v166, v166
	v_exp_f32_e32 v167, v167
	v_exp_f32_e32 v173, v173
	v_mul_f32_e32 v174, 0xbfb8aa3b, v174
	v_mul_f32_e32 v175, 0xbfb8aa3b, v175
	v_mul_f32_e32 v177, 0xbfb8aa3b, v177
	v_mul_f32_e32 v181, 0xbfb8aa3b, v181
	v_mul_f32_e32 v183, 0xbfb8aa3b, v183
	v_exp_f32_e32 v174, v174
	v_exp_f32_e32 v175, v175
	v_exp_f32_e32 v177, v177
	v_exp_f32_e32 v181, v181
	v_exp_f32_e32 v183, v183
	v_add_f32_e32 v166, 1.0, v166
	v_add_f32_e32 v167, 1.0, v167
	v_add_f32_e32 v173, 1.0, v173
	v_rcp_f32_e32 v166, v166
	v_rcp_f32_e32 v167, v167
	v_rcp_f32_e32 v173, v173
	v_add_f32_e32 v174, 1.0, v174
	v_add_f32_e32 v175, 1.0, v175
	v_add_f32_e32 v177, 1.0, v177
	v_add_f32_e32 v181, 1.0, v181
	v_add_f32_e32 v183, 1.0, v183
	v_rcp_f32_e32 v174, v174
	v_rcp_f32_e32 v175, v175
	v_rcp_f32_e32 v177, v177
	v_rcp_f32_e32 v181, v181
	v_rcp_f32_e32 v183, v183
	v_add_u32_e32 v148, 0xa0, v162
	v_ashrrev_i32_e32 v163, 31, v148
	v_mul_f32_e32 v166, 0xbf1b4598, v166
	v_mul_f32_e32 v167, 0xbf1b4598, v167
	v_mul_f32_e32 v173, 0xbf1b4598, v173
	v_mul_f32_e32 v174, 0xbf1b4598, v174
	v_mul_f32_e32 v175, 0xbf1b4598, v175
	v_mul_f32_e32 v177, 0xbf1b4598, v177
	v_mul_f32_e32 v181, 0xbf1b4598, v181
	v_mul_f32_e32 v183, 0xbf1b4598, v183
	v_cvt_pk_bf16_f32 v190, v166, v167
	v_cvt_pk_bf16_f32 v191, v173, v174
	v_mul_lo_u32 v163, s28, v163
	v_mul_lo_u32 v173, s29, v148
	v_mad_u64_u32 v[166:167], s[10:11], s28, v148, 0
	v_cvt_pk_bf16_f32 v192, v175, v177
	v_cvt_pk_bf16_f32 v193, v181, v183
	v_add3_u32 v167, v167, v163, v173
	v_add_f32_e32 v148, v12, v132
	v_add_f32_e32 v163, v13, v133
	v_add_f32_e32 v173, v14, v134
	v_add_f32_e32 v174, v15, v135
	v_add_f32_e32 v175, v4, v128
	v_add_f32_e32 v177, v5, v129
	v_add_f32_e32 v181, v6, v130
	v_add_f32_e32 v183, v7, v131
	v_add_f32_e32 v136, v16, v136
	v_mul_f32_e32 v148, 0xbfb8aa3b, v148
	v_mul_f32_e32 v163, 0xbfb8aa3b, v163
	v_mul_f32_e32 v173, 0xbfb8aa3b, v173
	v_mul_f32_e32 v174, 0xbfb8aa3b, v174
	v_mul_f32_e32 v175, 0xbfb8aa3b, v175
	v_mul_f32_e32 v177, 0xbfb8aa3b, v177
	v_mul_f32_e32 v181, 0xbfb8aa3b, v181
	v_mul_f32_e32 v183, 0xbfb8aa3b, v183
	v_mul_f32_e32 v136, 0xbfb8aa3b, v136
	v_exp_f32_e32 v148, v148
	v_exp_f32_e32 v163, v163
	v_exp_f32_e32 v173, v173
	v_exp_f32_e32 v174, v174
	v_exp_f32_e32 v175, v175
	v_exp_f32_e32 v177, v177
	v_exp_f32_e32 v181, v181
	v_exp_f32_e32 v183, v183
	v_exp_f32_e32 v136, v136
	v_add_f32_e32 v148, 1.0, v148
	v_add_f32_e32 v163, 1.0, v163
	v_add_f32_e32 v173, 1.0, v173
	v_add_f32_e32 v174, 1.0, v174
	v_add_f32_e32 v175, 1.0, v175
	v_add_f32_e32 v177, 1.0, v177
	v_add_f32_e32 v181, 1.0, v181
	v_add_f32_e32 v183, 1.0, v183
	v_add_f32_e32 v136, 1.0, v136
	v_rcp_f32_e32 v148, v148
	v_rcp_f32_e32 v163, v163
	v_rcp_f32_e32 v173, v173
	v_rcp_f32_e32 v174, v174
	v_rcp_f32_e32 v175, v175
	v_rcp_f32_e32 v177, v177
	v_rcp_f32_e32 v181, v181
	v_rcp_f32_e32 v183, v183
	v_rcp_f32_e32 v136, v136
	v_lshl_add_u64 v[166:167], v[166:167], 1, s[70:71]
	v_lshl_add_u64 v[166:167], v[166:167], 0, v[164:165]
	global_store_dwordx4 v[166:167], v[190:193], off nt
	v_mul_f32_e32 v148, 0xbf1b4598, v148
	v_mul_f32_e32 v163, 0xbf1b4598, v163
	v_mul_f32_e32 v173, 0xbf1b4598, v173
	v_mul_f32_e32 v174, 0xbf1b4598, v174
	v_mul_f32_e32 v175, 0xbf1b4598, v175
	v_mul_f32_e32 v177, 0xbf1b4598, v177
	v_mul_f32_e32 v181, 0xbf1b4598, v181
	v_mul_f32_e32 v183, 0xbf1b4598, v183
	v_cvt_pk_bf16_f32 v190, v148, v163
	v_cvt_pk_bf16_f32 v191, v173, v174
	v_cvt_pk_bf16_f32 v192, v175, v177
	v_cvt_pk_bf16_f32 v193, v181, v183
	global_store_dwordx4 v[166:167], v[190:193], off offset:256 nt
	v_mul_f32_e32 v166, 0xbf1b4598, v136
	v_add_f32_e32 v136, v17, v137
	v_mul_f32_e32 v136, 0xbfb8aa3b, v136
	v_exp_f32_e32 v136, v136
	v_add_f32_e32 v140, v24, v140
	v_add_f32_e32 v141, v25, v141
	v_add_f32_e32 v142, v26, v142
	v_add_f32_e32 v136, 1.0, v136
	v_rcp_f32_e32 v136, v136
	v_add_f32_e32 v143, v27, v143
	v_mul_f32_e32 v140, 0xbfb8aa3b, v140
	v_mul_f32_e32 v141, 0xbfb8aa3b, v141
	v_mul_f32_e32 v167, 0xbf1b4598, v136
	v_add_f32_e32 v136, v18, v138
	v_mul_f32_e32 v136, 0xbfb8aa3b, v136
	v_exp_f32_e32 v136, v136
	v_mul_f32_e32 v142, 0xbfb8aa3b, v142
	v_mul_f32_e32 v143, 0xbfb8aa3b, v143
	v_exp_f32_e32 v140, v140
	v_add_f32_e32 v136, 1.0, v136
	v_rcp_f32_e32 v136, v136
	v_exp_f32_e32 v141, v141
	v_exp_f32_e32 v142, v142
	v_exp_f32_e32 v143, v143
	v_mul_f32_e32 v173, 0xbf1b4598, v136
	v_add_f32_e32 v136, v19, v139
	v_mul_f32_e32 v136, 0xbfb8aa3b, v136
	v_exp_f32_e32 v136, v136
	v_add_f32_e32 v128, v0, v128
	v_add_f32_e32 v140, 1.0, v140
	v_add_f32_e32 v141, 1.0, v141
	v_add_f32_e32 v142, 1.0, v142
	v_add_f32_e32 v143, 1.0, v143
	v_mul_f32_e32 v128, 0xbfb8aa3b, v128
	v_rcp_f32_e32 v140, v140
	v_rcp_f32_e32 v141, v141
	v_rcp_f32_e32 v142, v142
	v_rcp_f32_e32 v143, v143
	v_add_f32_e32 v136, 1.0, v136
	v_exp_f32_e32 v128, v128
	v_rcp_f32_e32 v136, v136
	v_add_u32_e32 v148, 0xb0, v162
	v_ashrrev_i32_e32 v163, 31, v148
	v_mul_f32_e32 v140, 0xbf1b4598, v140
	v_mul_f32_e32 v141, 0xbf1b4598, v141
	v_mul_f32_e32 v142, 0xbf1b4598, v142
	v_mul_f32_e32 v143, 0xbf1b4598, v143
	v_add_f32_e32 v128, 1.0, v128
	v_mul_f32_e32 v139, 0xbf1b4598, v136
	v_cvt_pk_bf16_f32 v136, v140, v141
	v_cvt_pk_bf16_f32 v137, v142, v143
	v_mul_lo_u32 v142, s28, v163
	v_mul_lo_u32 v143, s29, v148
	v_mad_u64_u32 v[140:141], s[10:11], s28, v148, 0
	v_rcp_f32_e32 v128, v128
	v_add3_u32 v141, v141, v142, v143
	v_lshl_add_u64 v[140:141], v[140:141], 1, s[70:71]
	v_lshl_add_u64 v[140:141], v[140:141], 0, v[164:165]
	v_cvt_pk_bf16_f32 v138, v166, v167
	v_cvt_pk_bf16_f32 v139, v173, v139
	global_store_dwordx4 v[140:141], v[136:139], off nt
	v_add_f32_e32 v132, v8, v132
	v_add_f32_e32 v133, v9, v133
	v_mul_f32_e32 v136, 0xbf1b4598, v128
	v_add_f32_e32 v128, v1, v129
	v_mul_f32_e32 v128, 0xbfb8aa3b, v128
	v_exp_f32_e32 v128, v128
	v_add_f32_e32 v134, v10, v134
	v_add_f32_e32 v135, v11, v135
	v_mul_f32_e32 v132, 0xbfb8aa3b, v132
	v_add_f32_e32 v128, 1.0, v128
	v_rcp_f32_e32 v128, v128
	v_mul_f32_e32 v133, 0xbfb8aa3b, v133
	v_mul_f32_e32 v134, 0xbfb8aa3b, v134
	v_mul_f32_e32 v135, 0xbfb8aa3b, v135
	v_mul_f32_e32 v137, 0xbf1b4598, v128
	v_add_f32_e32 v128, v2, v130
	v_mul_f32_e32 v128, 0xbfb8aa3b, v128
	v_exp_f32_e32 v128, v128
	v_exp_f32_e32 v132, v132
	v_exp_f32_e32 v133, v133
	v_exp_f32_e32 v134, v134
	v_add_f32_e32 v128, 1.0, v128
	v_rcp_f32_e32 v128, v128
	v_exp_f32_e32 v135, v135
	v_add_f32_e32 v132, 1.0, v132
	v_add_f32_e32 v133, 1.0, v133
	v_mul_f32_e32 v138, 0xbf1b4598, v128
	v_add_f32_e32 v128, v3, v131
	v_mul_f32_e32 v128, 0xbfb8aa3b, v128
	v_exp_f32_e32 v128, v128
	v_add_f32_e32 v134, 1.0, v134
	v_add_f32_e32 v135, 1.0, v135
	v_rcp_f32_e32 v132, v132
	v_add_f32_e32 v128, 1.0, v128
	v_rcp_f32_e32 v128, v128
	v_rcp_f32_e32 v133, v133
	v_rcp_f32_e32 v134, v134
	v_rcp_f32_e32 v135, v135
	v_mul_f32_e32 v131, 0xbf1b4598, v128
	v_mul_f32_e32 v132, 0xbf1b4598, v132
	v_mul_f32_e32 v133, 0xbf1b4598, v133
	v_mul_f32_e32 v134, 0xbf1b4598, v134
	v_mul_f32_e32 v135, 0xbf1b4598, v135
	v_cvt_pk_bf16_f32 v128, v132, v133
	v_cvt_pk_bf16_f32 v129, v134, v135
	v_cvt_pk_bf16_f32 v130, v136, v137
	v_cvt_pk_bf16_f32 v131, v138, v131
	global_store_dwordx4 v[140:141], v[128:131], off offset:256 nt

.LBB0_534:
	s_andn2_b64 vcc, exec, s[10:11]
	s_cbranch_vccnz .LBB0_536
	v_ashrrev_i32_e32 v163, 31, v162
	v_lshlrev_b64 v[128:129], 6, v[162:163]
	v_lshl_add_u64 v[132:133], v[156:157], 0, v[128:129]
	global_load_dwordx4 v[128:131], v[132:133], off
	global_load_dwordx4 v[136:139], v[132:133], off offset:1024
	global_load_dwordx4 v[164:167], v[132:133], off offset:2048
	global_load_dwordx4 v[190:193], v[132:133], off offset:3072
	v_lshl_or_b32 v134, s25, 8, v186
	v_add_u32_e32 v174, 0x80, v162
	v_ashrrev_i32_e32 v175, 31, v174
	s_waitcnt vmcnt(0)
	v_mov_b32_e32 v132, v129
	v_mov_b32_e32 v133, v130
	v_mov_b32_e32 v129, v131
	v_pk_add_f32 v[128:129], v[132:133], v[128:129]
	v_mov_b32_e32 v132, v137
	v_pk_add_f32 v[128:129], v[128:129], v[128:129] op_sel:[0,1] op_sel_hi:[1,0]
	v_mov_b32_e32 v133, v138
	v_mov_b32_e32 v137, v139
	v_mov_b32_e32 v129, v128
	v_pk_add_f32 v[132:133], v[132:133], v[136:137]
	s_nop 0
	v_permlane16_swap_b32_e32 v128, v129
	v_pk_add_f32 v[132:133], v[132:133], v[132:133] op_sel:[0,1] op_sel_hi:[1,0]
	v_add_f32_e32 v129, v128, v129
	v_mov_b32_e32 v128, v132
	s_nop 1
	v_permlane16_swap_b32_e32 v132, v128
	v_add_f32_e32 v128, v132, v128
	v_mov_b32_e32 v131, v129
	v_mov_b32_e32 v130, v128
	s_nop 0
	v_permlane32_swap_b32_e32 v129, v131
	v_permlane32_swap_b32_e32 v128, v130
	v_pk_add_f32 v[128:129], v[128:129], v[130:131]
	v_mov_b64_e32 v[132:133], s[56:57]
	v_pk_fma_f32 v[128:129], v[128:129], s[54:55], v[132:133] op_sel_hi:[1,0,0]
	v_mov_b32_e32 v136, v191
	v_mul_f32_e32 v130, 0x4b800000, v129
	v_cmp_gt_f32_e64 s[10:11], s88, v129
	v_cmp_gt_f32_e32 vcc, s88, v128
	v_mov_b32_e32 v137, v192
	v_cndmask_b32_e64 v129, v129, v130, s[10:11]
	v_rsq_f32_e32 v129, v129
	v_mov_b32_e32 v191, v193
	v_pk_add_f32 v[136:137], v[136:137], v[190:191]
	v_mul_f32_e32 v130, 0x45800000, v129
	v_cndmask_b32_e64 v141, v129, v130, s[10:11]
	v_mul_f32_e32 v129, 0x4b800000, v128
	v_cndmask_b32_e32 v128, v128, v129, vcc
	v_rsq_f32_e32 v128, v128
	v_pk_add_f32 v[136:137], v[136:137], v[136:137] op_sel:[0,1] op_sel_hi:[1,0]
	v_mul_f32_e32 v135, v116, v141
	v_mul_f32_e32 v137, v118, v141
	v_mul_f32_e32 v129, 0x45800000, v128
	v_cndmask_b32_e32 v140, v128, v129, vcc
	v_mov_b32_e32 v128, v165
	v_mov_b32_e32 v129, v166
	v_mov_b32_e32 v165, v167
	v_pk_add_f32 v[128:129], v[128:129], v[164:165]
	v_mul_f32_e32 v142, v119, v141
	v_pk_add_f32 v[128:129], v[128:129], v[128:129] op_sel:[0,1] op_sel_hi:[1,0]
	v_mul_f32_e32 v143, v100, v141
	v_mov_b32_e32 v129, v128
	s_nop 1
	v_permlane16_swap_b32_e32 v128, v129
	v_add_f32_e32 v129, v128, v129
	v_mov_b32_e32 v128, v136
	s_nop 1
	v_permlane16_swap_b32_e32 v136, v128
	v_add_f32_e32 v128, v136, v128
	v_mov_b32_e32 v131, v129
	v_mov_b32_e32 v130, v128
	s_nop 0
	v_permlane32_swap_b32_e32 v129, v131
	v_permlane32_swap_b32_e32 v128, v130
	v_pk_add_f32 v[128:129], v[128:129], v[130:131]
	v_mul_f32_e32 v131, v127, v141
	v_pk_fma_f32 v[128:129], v[128:129], s[54:55], v[132:133] op_sel_hi:[1,0,0]
	v_mul_f32_e32 v136, v117, v141
	v_mul_f32_e32 v130, 0x4b800000, v129
	v_cmp_gt_f32_e64 s[10:11], s88, v129
	v_cmp_gt_f32_e32 vcc, s88, v128
	v_mul_f32_e32 v148, v101, v141
	v_cndmask_b32_e64 v129, v129, v130, s[10:11]
	v_rsq_f32_e32 v129, v129
	s_nop 0
	v_mul_f32_e32 v130, 0x45800000, v129
	v_cndmask_b32_e64 v139, v129, v130, s[10:11]
	v_mul_f32_e32 v129, 0x4b800000, v128
	v_cndmask_b32_e32 v128, v128, v129, vcc
	v_rsq_f32_e32 v128, v128
	v_mul_f32_e32 v130, v126, v141
	v_mul_f32_e32 v129, 0x45800000, v128
	v_cndmask_b32_e32 v138, v128, v129, vcc
	v_mul_f32_e32 v128, v124, v141
	v_mul_f32_e32 v129, v125, v141
	v_cvt_pk_bf16_f32 v128, v128, v129
	v_cvt_pk_bf16_f32 v129, v130, v131
	v_cvt_pk_bf16_f32 v130, v135, v136
	v_cvt_pk_bf16_f32 v131, v137, v142
	v_mul_lo_u32 v135, s29, v162
	v_mul_lo_u32 v142, s28, v163
	v_mad_u64_u32 v[136:137], s[10:11], s28, v162, 0
	v_add3_u32 v137, v137, v142, v135
	v_ashrrev_i32_e32 v135, 31, v134
	v_lshl_add_u64 v[136:137], v[136:137], 1, s[70:71]
	v_lshlrev_b64 v[134:135], 1, v[134:135]
	v_lshl_add_u64 v[136:137], v[136:137], 0, v[134:135]
	global_store_dwordx4 v[136:137], v[128:131], off nt
	v_mul_f32_e32 v163, v102, v141
	s_nop 0
	v_mul_f32_e32 v128, v108, v141
	v_mul_f32_e32 v129, v109, v141
	v_mul_f32_e32 v130, v110, v141
	v_mul_f32_e32 v131, v111, v141
	v_mul_f32_e32 v141, v103, v141
	v_cvt_pk_bf16_f32 v128, v128, v129
	v_cvt_pk_bf16_f32 v129, v130, v131
	v_cvt_pk_bf16_f32 v130, v143, v148
	v_cvt_pk_bf16_f32 v131, v163, v141
	global_store_dwordx4 v[136:137], v[128:131], off offset:256 nt
	v_or_b32_e32 v136, 16, v162
	v_mul_f32_e32 v137, v112, v140
	v_mul_f32_e32 v128, v120, v140
	v_mul_f32_e32 v129, v121, v140
	v_mul_f32_e32 v130, v122, v140
	v_mul_f32_e32 v141, v113, v140
	v_mul_f32_e32 v131, v123, v140
	v_cvt_pk_bf16_f32 v128, v128, v129
	v_cvt_pk_bf16_f32 v129, v130, v131
	v_cvt_pk_bf16_f32 v130, v137, v141
	v_mul_lo_u32 v141, s29, v136
	v_mad_u64_u32 v[136:137], s[10:11], s28, v136, 0
	v_add3_u32 v137, v137, v142, v141
	v_lshl_add_u64 v[136:137], v[136:137], 1, s[70:71]
	v_lshl_add_u64 v[136:137], v[136:137], 0, v[134:135]
	v_mul_f32_e32 v143, v114, v140
	v_mul_f32_e32 v148, v115, v140
	v_cvt_pk_bf16_f32 v131, v143, v148
	global_store_dwordx4 v[136:137], v[128:131], off nt
	v_mul_f32_e32 v141, v96, v140
	v_mul_f32_e32 v143, v97, v140
	v_mul_f32_e32 v128, v104, v140
	v_mul_f32_e32 v129, v105, v140
	v_mul_f32_e32 v130, v106, v140
	v_mul_f32_e32 v131, v107, v140
	v_mul_f32_e32 v148, v98, v140
	v_mul_f32_e32 v140, v99, v140
	v_cvt_pk_bf16_f32 v128, v128, v129
	v_cvt_pk_bf16_f32 v129, v130, v131
	v_cvt_pk_bf16_f32 v130, v141, v143
	v_cvt_pk_bf16_f32 v131, v148, v140
	global_store_dwordx4 v[136:137], v[128:131], off offset:256 nt
	v_or_b32_e32 v136, 32, v162
	v_mul_f32_e32 v137, v84, v139
	v_mul_f32_e32 v128, v92, v139
	v_mul_f32_e32 v129, v93, v139
	v_mul_f32_e32 v130, v94, v139
	v_mul_f32_e32 v140, v85, v139
	v_mul_f32_e32 v131, v95, v139
	v_cvt_pk_bf16_f32 v128, v128, v129
	v_cvt_pk_bf16_f32 v129, v130, v131
	v_cvt_pk_bf16_f32 v130, v137, v140
	v_mul_lo_u32 v140, s29, v136
	v_mad_u64_u32 v[136:137], s[10:11], s28, v136, 0
	v_add3_u32 v137, v137, v142, v140
	v_lshl_add_u64 v[136:137], v[136:137], 1, s[70:71]
	v_lshl_add_u64 v[136:137], v[136:137], 0, v[134:135]
	v_mul_f32_e32 v141, v86, v139
	v_mul_f32_e32 v143, v87, v139
	v_cvt_pk_bf16_f32 v131, v141, v143
	global_store_dwordx4 v[136:137], v[128:131], off nt
	v_mul_f32_e32 v140, v68, v139
	v_mul_f32_e32 v141, v69, v139
	v_mul_f32_e32 v128, v76, v139
	v_mul_f32_e32 v129, v77, v139
	v_mul_f32_e32 v130, v78, v139
	v_mul_f32_e32 v131, v79, v139
	v_mul_f32_e32 v143, v70, v139
	v_mul_f32_e32 v139, v71, v139
	v_cvt_pk_bf16_f32 v128, v128, v129
	v_cvt_pk_bf16_f32 v129, v130, v131
	v_cvt_pk_bf16_f32 v130, v140, v141
	v_cvt_pk_bf16_f32 v131, v143, v139
	global_store_dwordx4 v[136:137], v[128:131], off offset:256 nt
	v_or_b32_e32 v136, 48, v162
	v_mul_f32_e32 v137, v80, v138
	v_mul_f32_e32 v128, v88, v138
	v_mul_f32_e32 v129, v89, v138
	v_mul_f32_e32 v130, v90, v138
	v_mul_f32_e32 v139, v81, v138
	v_mul_f32_e32 v131, v91, v138
	v_cvt_pk_bf16_f32 v128, v128, v129
	v_cvt_pk_bf16_f32 v129, v130, v131
	v_cvt_pk_bf16_f32 v130, v137, v139
	v_mul_lo_u32 v139, s29, v136
	v_mad_u64_u32 v[136:137], s[10:11], s28, v136, 0
	v_add3_u32 v137, v137, v142, v139
	v_lshl_add_u64 v[136:137], v[136:137], 1, s[70:71]
	v_lshl_add_u64 v[136:137], v[136:137], 0, v[134:135]
	v_mul_f32_e32 v140, v82, v138
	v_mul_f32_e32 v141, v83, v138
	v_cvt_pk_bf16_f32 v131, v140, v141
	global_store_dwordx4 v[136:137], v[128:131], off nt
	v_mul_f32_e32 v139, v64, v138
	v_mul_f32_e32 v140, v65, v138
	v_mul_f32_e32 v128, v72, v138
	v_mul_f32_e32 v129, v73, v138
	v_mul_f32_e32 v130, v74, v138
	v_mul_f32_e32 v131, v75, v138
	v_cvt_pk_bf16_f32 v128, v128, v129
	v_cvt_pk_bf16_f32 v129, v130, v131
	v_mul_f32_e32 v141, v66, v138
	v_mul_f32_e32 v138, v67, v138
	v_cvt_pk_bf16_f32 v130, v139, v140
	v_cvt_pk_bf16_f32 v131, v141, v138
	global_store_dwordx4 v[136:137], v[128:131], off offset:256 nt
	s_nop 1
	v_lshlrev_b64 v[128:129], 6, v[174:175]
	v_lshl_add_u64 v[190:191], v[156:157], 0, v[128:129]
	global_load_dwordx4 v[128:131], v[190:191], off
	global_load_dwordx4 v[136:139], v[190:191], off offset:1024
	global_load_dwordx4 v[140:143], v[190:191], off offset:2048
	global_load_dwordx4 v[164:167], v[190:191], off offset:3072
	s_waitcnt vmcnt(0)
	v_mov_b32_e32 v190, v129
	v_mov_b32_e32 v191, v130
	v_mov_b32_e32 v129, v131
	v_pk_add_f32 v[128:129], v[190:191], v[128:129]
	v_mov_b32_e32 v190, v137
	v_pk_add_f32 v[128:129], v[128:129], v[128:129] op_sel:[0,1] op_sel_hi:[1,0]
	v_mov_b32_e32 v191, v138
	v_mov_b32_e32 v137, v139
	v_mov_b32_e32 v129, v128
	v_pk_add_f32 v[136:137], v[190:191], v[136:137]
	s_nop 0
	v_permlane16_swap_b32_e32 v128, v129
	v_pk_add_f32 v[136:137], v[136:137], v[136:137] op_sel:[0,1] op_sel_hi:[1,0]
	v_add_f32_e32 v129, v128, v129
	v_mov_b32_e32 v128, v136
	s_nop 1
	v_permlane16_swap_b32_e32 v136, v128
	v_add_f32_e32 v128, v136, v128
	v_mov_b32_e32 v131, v129
	v_mov_b32_e32 v130, v128
	s_nop 0
	v_permlane32_swap_b32_e32 v129, v131
	v_permlane32_swap_b32_e32 v128, v130
	v_pk_add_f32 v[128:129], v[128:129], v[130:131]
	v_mov_b32_e32 v136, v165
	v_pk_fma_f32 v[128:129], v[128:129], s[54:55], v[132:133] op_sel_hi:[1,0,0]
	v_mov_b32_e32 v137, v166
	v_mul_f32_e32 v130, 0x4b800000, v129
	v_cmp_gt_f32_e64 s[10:11], s88, v129
	v_cmp_gt_f32_e32 vcc, s88, v128
	v_mov_b32_e32 v165, v167
	v_cndmask_b32_e64 v129, v129, v130, s[10:11]
	v_rsq_f32_e32 v129, v129
	v_pk_add_f32 v[136:137], v[136:137], v[164:165]
	v_mul_f32_e32 v130, 0x45800000, v129
	v_cndmask_b32_e64 v138, v129, v130, s[10:11]
	v_mul_f32_e32 v129, 0x4b800000, v128
	v_cndmask_b32_e32 v128, v128, v129, vcc
	v_rsq_f32_e32 v128, v128
	v_pk_add_f32 v[136:137], v[136:137], v[136:137] op_sel:[0,1] op_sel_hi:[1,0]
	v_mul_f32_e32 v129, 0x45800000, v128
	v_cndmask_b32_e32 v139, v128, v129, vcc
	v_mov_b32_e32 v128, v141
	v_mov_b32_e32 v129, v142
	v_mov_b32_e32 v141, v143
	v_pk_add_f32 v[128:129], v[128:129], v[140:141]
	v_mul_f32_e32 v140, v58, v138
	v_pk_add_f32 v[128:129], v[128:129], v[128:129] op_sel:[0,1] op_sel_hi:[1,0]
	v_mul_f32_e32 v141, v59, v138
	v_mov_b32_e32 v129, v128
	s_nop 1
	v_permlane16_swap_b32_e32 v128, v129
	v_add_f32_e32 v129, v128, v129
	v_mov_b32_e32 v128, v136
	s_nop 1
	v_permlane16_swap_b32_e32 v136, v128
	v_add_f32_e32 v128, v136, v128
	v_mov_b32_e32 v131, v129
	v_mov_b32_e32 v130, v128
	s_nop 0
	v_permlane32_swap_b32_e32 v129, v131
	v_permlane32_swap_b32_e32 v128, v130
	v_pk_add_f32 v[128:129], v[128:129], v[130:131]
	v_mul_f32_e32 v131, v63, v138
	v_pk_fma_f32 v[128:129], v[128:129], s[54:55], v[132:133] op_sel_hi:[1,0,0]
	v_mul_f32_e32 v132, v56, v138
	v_mul_f32_e32 v130, 0x4b800000, v129
	v_cmp_gt_f32_e64 s[10:11], s88, v129
	v_cmp_gt_f32_e32 vcc, s88, v128
	v_mul_f32_e32 v133, v57, v138
	v_cndmask_b32_e64 v129, v129, v130, s[10:11]
	v_rsq_f32_e32 v129, v129
	v_mul_f32_e32 v142, v38, v138
	v_mul_f32_e32 v130, 0x45800000, v129
	v_cndmask_b32_e64 v136, v129, v130, s[10:11]
	v_mul_f32_e32 v129, 0x4b800000, v128
	v_cndmask_b32_e32 v128, v128, v129, vcc
	v_rsq_f32_e32 v128, v128
	v_mul_f32_e32 v130, v62, v138
	v_mul_f32_e32 v129, 0x45800000, v128
	v_cndmask_b32_e32 v137, v128, v129, vcc
	v_mul_f32_e32 v128, v60, v138
	v_mul_f32_e32 v129, v61, v138
	v_cvt_pk_bf16_f32 v128, v128, v129
	v_cvt_pk_bf16_f32 v129, v130, v131
	v_cvt_pk_bf16_f32 v130, v132, v133
	v_cvt_pk_bf16_f32 v131, v140, v141
	v_mul_lo_u32 v140, s28, v175
	v_mul_lo_u32 v141, s29, v174
	v_mad_u64_u32 v[132:133], s[10:11], s28, v174, 0
	v_add3_u32 v133, v133, v140, v141
	v_lshl_add_u64 v[132:133], v[132:133], 1, s[70:71]
	v_lshl_add_u64 v[132:133], v[132:133], 0, v[134:135]
	global_store_dwordx4 v[132:133], v[128:131], off nt
	v_mul_f32_e32 v140, v36, v138
	v_mul_f32_e32 v141, v37, v138
	v_mul_f32_e32 v128, v44, v138
	v_mul_f32_e32 v129, v45, v138
	v_mul_f32_e32 v130, v46, v138
	v_mul_f32_e32 v131, v47, v138
	v_mul_f32_e32 v138, v39, v138
	v_cvt_pk_bf16_f32 v128, v128, v129
	v_cvt_pk_bf16_f32 v129, v130, v131
	v_cvt_pk_bf16_f32 v130, v140, v141
	v_cvt_pk_bf16_f32 v131, v142, v138
	global_store_dwordx4 v[132:133], v[128:131], off offset:256 nt
	v_add_u32_e32 v132, 0x90, v162
	v_ashrrev_i32_e32 v133, 31, v132
	v_mul_f32_e32 v128, v52, v139
	v_mul_f32_e32 v129, v53, v139
	v_mul_f32_e32 v130, v54, v139
	v_mul_f32_e32 v138, v48, v139
	v_mul_f32_e32 v140, v49, v139
	v_mul_f32_e32 v131, v55, v139
	v_cvt_pk_bf16_f32 v128, v128, v129
	v_cvt_pk_bf16_f32 v129, v130, v131
	v_cvt_pk_bf16_f32 v130, v138, v140
	v_mul_lo_u32 v138, s28, v133
	v_mul_lo_u32 v140, s29, v132
	v_mad_u64_u32 v[132:133], s[10:11], s28, v132, 0
	v_add3_u32 v133, v133, v138, v140
	v_lshl_add_u64 v[132:133], v[132:133], 1, s[70:71]
	v_mul_f32_e32 v141, v50, v139
	v_mul_f32_e32 v142, v51, v139
	v_cvt_pk_bf16_f32 v131, v141, v142
	v_lshl_add_u64 v[132:133], v[132:133], 0, v[134:135]
	global_store_dwordx4 v[132:133], v[128:131], off nt
	v_mul_f32_e32 v138, v32, v139
	v_mul_f32_e32 v140, v33, v139
	v_mul_f32_e32 v128, v40, v139
	v_mul_f32_e32 v129, v41, v139
	v_mul_f32_e32 v130, v42, v139
	v_mul_f32_e32 v131, v43, v139
	v_mul_f32_e32 v141, v34, v139
	v_mul_f32_e32 v139, v35, v139
	v_cvt_pk_bf16_f32 v128, v128, v129
	v_cvt_pk_bf16_f32 v129, v130, v131
	v_cvt_pk_bf16_f32 v130, v138, v140
	v_cvt_pk_bf16_f32 v131, v141, v139
	global_store_dwordx4 v[132:133], v[128:131], off offset:256 nt
	v_add_u32_e32 v132, 0xa0, v162
	v_ashrrev_i32_e32 v133, 31, v132
	v_mul_f32_e32 v128, v28, v136
	v_mul_f32_e32 v129, v29, v136
	v_mul_f32_e32 v130, v30, v136
	v_mul_f32_e32 v138, v20, v136
	v_mul_f32_e32 v139, v21, v136
	v_mul_f32_e32 v131, v31, v136
	v_cvt_pk_bf16_f32 v128, v128, v129
	v_cvt_pk_bf16_f32 v129, v130, v131
	v_cvt_pk_bf16_f32 v130, v138, v139
	v_mul_lo_u32 v138, s28, v133
	v_mul_lo_u32 v139, s29, v132
	v_mad_u64_u32 v[132:133], s[10:11], s28, v132, 0
	v_add3_u32 v133, v133, v138, v139
	v_lshl_add_u64 v[132:133], v[132:133], 1, s[70:71]
	v_mul_f32_e32 v140, v22, v136
	v_mul_f32_e32 v141, v23, v136
	v_cvt_pk_bf16_f32 v131, v140, v141
	v_lshl_add_u64 v[132:133], v[132:133], 0, v[134:135]
	global_store_dwordx4 v[132:133], v[128:131], off nt
	v_mul_f32_e32 v138, v4, v136
	v_mul_f32_e32 v139, v5, v136
	v_mul_f32_e32 v128, v12, v136
	v_mul_f32_e32 v129, v13, v136
	v_mul_f32_e32 v130, v14, v136
	v_mul_f32_e32 v131, v15, v136
	v_mul_f32_e32 v140, v6, v136
	v_mul_f32_e32 v136, v7, v136
	v_cvt_pk_bf16_f32 v128, v128, v129
	v_cvt_pk_bf16_f32 v129, v130, v131
	v_cvt_pk_bf16_f32 v130, v138, v139
	v_cvt_pk_bf16_f32 v131, v140, v136
	global_store_dwordx4 v[132:133], v[128:131], off offset:256 nt
	v_add_u32_e32 v132, 0xb0, v162
	v_ashrrev_i32_e32 v133, 31, v132
	v_mul_f32_e32 v128, v24, v137
	v_mul_f32_e32 v129, v25, v137
	v_mul_f32_e32 v130, v26, v137
	v_mul_f32_e32 v136, v16, v137
	v_mul_f32_e32 v138, v17, v137
	v_mul_f32_e32 v131, v27, v137
	v_cvt_pk_bf16_f32 v128, v128, v129
	v_cvt_pk_bf16_f32 v129, v130, v131
	v_cvt_pk_bf16_f32 v130, v136, v138
	v_mul_lo_u32 v136, s28, v133
	v_mul_lo_u32 v138, s29, v132
	v_mad_u64_u32 v[132:133], s[10:11], s28, v132, 0
	v_add3_u32 v133, v133, v136, v138
	v_lshl_add_u64 v[132:133], v[132:133], 1, s[70:71]
	v_mul_f32_e32 v139, v18, v137
	v_mul_f32_e32 v140, v19, v137
	v_cvt_pk_bf16_f32 v131, v139, v140
	v_lshl_add_u64 v[132:133], v[132:133], 0, v[134:135]
	global_store_dwordx4 v[132:133], v[128:131], off nt
	v_mul_f32_e32 v134, v0, v137
	v_mul_f32_e32 v135, v1, v137
	v_mul_f32_e32 v128, v8, v137
	v_mul_f32_e32 v129, v9, v137
	v_mul_f32_e32 v130, v10, v137
	v_mul_f32_e32 v131, v11, v137
	v_mul_f32_e32 v136, v2, v137
	v_mul_f32_e32 v137, v3, v137
	v_cvt_pk_bf16_f32 v128, v128, v129
	v_cvt_pk_bf16_f32 v129, v130, v131
	v_cvt_pk_bf16_f32 v130, v134, v135
	v_cvt_pk_bf16_f32 v131, v136, v137
	global_store_dwordx4 v[132:133], v[128:131], off offset:256 nt
